# XCD-aware tile order in w_out/w_down phases (column tiles of one row block on one XCD) + packed-f32 scan + pipelined attention PV reads
# speedup vs baseline: 1.1590x; 1.0409x over previous
; __device__ __forceinline__ unsigned char* WS(const Params& p) { unsigned z = 0; asm volatile("" : "+s"(z)); return p.ws + z; }
; __device__ __forceinline__ void run_phase(const Params& p, int ph, char* lds, int mode) {
;     ...
;   const int l = (ph - 1) / 7, sp = (ph - 1) % 7;
;   const float* xin = (l == 0) ? p.x : p.out;
;   switch (sp) {
;     ...
;     case 6: {
;       for (int it = B; it < 1024; it += G) { if (EN(60)) gemm_RES((const bf16_t*)(WS(p) + OFF_U), DFF, (const bf16_t*)(WS(p) + OFF_WDN), p.out, p.out, (bf16_t*)(WS(p) + OFF_XB), (float*)(WS(p) + OFF_RSS), it, lds); __syncthreads(); }
.LBB0_87:
	s_add_i32 s3, s2, -1
	s_mul_hi_i32 s24, s3, 0x92492493
	s_add_i32 s24, s24, s3
	s_lshr_b32 s25, s24, 31
	s_ashr_i32 s24, s24, 2
	s_add_i32 s64, s24, s25
	s_mul_i32 s24, s64, 7
	s_sub_i32 s3, s3, s24
	s_add_i32 s2, s2, 5
	s_cmp_lt_u32 s2, 13
	s_cselect_b64 s[4:5], -1, 0
	v_writelane_b32 v255, s4, 11
	s_cmp_lt_i32 s3, 3
	s_mov_b64 s[24:25], -1
	v_writelane_b32 v255, s5, 12
	v_writelane_b32 v255, s3, 13
	s_cbranch_scc1 .LBB0_152
	v_readlane_b32 s2, v255, 13
	s_cmp_lt_i32 s2, 5
	s_cbranch_scc1 .LBB0_112
	v_readlane_b32 s2, v255, 13
	s_cmp_lt_i32 s2, 6
	s_cbranch_scc1 .LBB0_105
	v_readlane_b32 s2, v255, 13
	s_cmp_eq_u32 s2, 6
	s_cbranch_scc0 .LBB0_104
	v_readlane_b32 s2, v254, 5
	v_readlane_b32 s3, v254, 6
	s_andn2_b64 vcc, exec, s[2:3]
	s_cbranch_vccnz .LBB0_104
	s_waitcnt lgkmcnt(0)
	s_lshl_b32 s30, s77, 4
	s_lshl_b32 s31, s77, 7
	v_readlane_b32 s34, v254, 43
	v_readlane_b32 s35, v254, 58
	v_readlane_b32 s36, v252, 0
	s_nop 0
	s_and_b32 s2, s36, 7
	s_lshl_b32 s2, s2, 3
	s_bfe_u32 s3, s36, 0x30003
	s_or_b32 s2, s2, s3
	s_andn2_b32 s36, s36, 63
	s_or_b32 s36, s36, s2
	s_lshl_b32 s35, s36, 4
	s_lshl_b32 s34, s36, 7
	s_branch .LBB0_94

; __device__ __forceinline__ unsigned char* WS(const Params& p) { unsigned z = 0; asm volatile("" : "+s"(z)); return p.ws + z; }
; __device__ __forceinline__ int opaque_tid() { int t = threadIdx.x; asm volatile("" : "+v"(t)); return t; }
; __device__ __forceinline__ void gemm_RES(const bf16_t* A, int K, const bf16_t* Bt, const float* xin, float* xout, bf16_t* xb, float* rss, int item, char* lds) {
;   const int mt = item >> 3, nt = item & 7; const int m0 = mt * 128, n0 = nt * 128;
; __device__ __forceinline__ void run_phase(const Params& p, int ph, char* lds, int mode) {
;     ...
;     case 4: {
;       { float* z = (float*)(WS(p) + OFF_RSS) + 2 * T; for (int i = B * NTHREADS + opaque_tid(); i < 2 * T; i += G * NTHREADS) z[i] = 0.f; }
;       const bf16_t* wo = (const bf16_t*)(WS(p) + ((l & 1) ? OFF_WOUT2 : OFF_WOUT));
;       for (int it = B; it < 1024; it += G) { if (EN(40)) gemm_RES((const bf16_t*)(WS(p) + OFF_Y), 1024, wo, xin, p.out, (bf16_t*)(WS(p) + OFF_XB), (float*)(WS(p) + OFF_RSS) + T, it, lds); __syncthreads(); }
.LBB0_122:
	s_or_b64 exec, exec, s[24:25]
	v_readlane_b32 s4, v254, 5
	v_readlane_b32 s5, v254, 6
	s_mov_b32 s2, s89
	s_andn2_b64 vcc, exec, s[4:5]
	s_cbranch_vccnz .LBB0_135
	s_add_u32 s3, s46, s2
	s_addc_u32 s25, s47, 0
	s_bitcmp0_b32 s64, 0
	s_mov_b32 s24, 0x568000
	s_cselect_b32 s28, s24, 0xf94c000
	s_add_u32 s24, s3, s28
	v_readlane_b32 s4, v255, 11
	s_addc_u32 s25, s25, 0
	v_readlane_b32 s5, v255, 12
	s_and_b64 s[26:27], s[4:5], exec
	v_readlane_b32 s4, v252, 35
	v_readlane_b32 s18, v252, 49
	v_readlane_b32 s19, v252, 50
	s_cselect_b32 s27, s49, s19
	s_cselect_b32 s26, s48, s18
	s_waitcnt lgkmcnt(0)
	s_lshl_b32 s38, s77, 4
	s_add_u32 s2, s28, s2
	s_addc_u32 s3, 0, 0
	v_readlane_b32 s4, v254, 51
	s_add_u32 s28, s4, s2
	v_readlane_b32 s2, v254, 52
	s_addc_u32 s29, s2, s3
	s_lshl_b32 s39, s77, 7
	v_readlane_b32 s40, v254, 43
	v_readlane_b32 s41, v254, 58
	v_readlane_b32 s42, v252, 0
	v_readlane_b32 s5, v252, 36
	v_readlane_b32 s6, v252, 37
	v_readlane_b32 s7, v252, 38
	v_readlane_b32 s8, v252, 39
	v_readlane_b32 s9, v252, 40
	v_readlane_b32 s10, v252, 41
	v_readlane_b32 s11, v252, 42
	v_readlane_b32 s12, v252, 43
	v_readlane_b32 s13, v252, 44
	v_readlane_b32 s14, v252, 45
	v_readlane_b32 s15, v252, 46
	v_readlane_b32 s16, v252, 47
	v_readlane_b32 s17, v252, 48
	s_nop 0
	s_and_b32 s2, s42, 7
	s_lshl_b32 s2, s2, 3
	s_bfe_u32 s3, s42, 0x30003
	s_or_b32 s2, s2, s3
	s_andn2_b32 s42, s42, 63
	s_or_b32 s42, s42, s2
	s_lshl_b32 s41, s42, 4
	s_lshl_b32 s40, s42, 7
	s_branch .LBB0_125

; __device__ __forceinline__ void attn_item(const Params& p, int l, int bh, int qt, char* lds) {
;     ...
;     if (active) {
; #pragma unroll
;       for (int nd = 0; nd < 8; nd++)
; #pragma unroll
;         for (int c2 = 0; c2 < 2; c2++) {
;           const int vrow_ = nd * 16 + fr;
;           const bf16x8 vf = *(const bf16x8*)(Vs + (vrow_ * 8 + ((c2 * 4 + fq) ^ ((vrow_ >> 1) & 7))) * 16);
;           o[0][nd] = __builtin_amdgcn_mfma_f32_16x16x32_bf16(vf, pf[0][c2], o[0][nd], 0, 0, 0);
;           o[1][nd] = __builtin_amdgcn_mfma_f32_16x16x32_bf16(vf, pf[1][c2], o[1][nd], 0, 0, 0);
;           if (c2 == 1) __builtin_amdgcn_sched_barrier(0);
;         }
;     }
.LBB0_413:
	s_barrier
	s_and_saveexec_b64 s[36:37], s[34:35]
	s_cbranch_execz .LBB0_415
	ds_read_b128 v[132:135], v245 offset:49152
	ds_read_b128 v[136:139], v246 offset:49152
	ds_read_b128 v[140:143], v247 offset:49152
	ds_read_b128 v[144:147], v248 offset:49152
	ds_read_b128 v[150:153], v249 offset:49152
	s_waitcnt lgkmcnt(4)
	v_mfma_f32_16x16x32_bf16 v[112:115], v[132:135], v[116:119], v[112:115]
	v_mfma_f32_16x16x32_bf16 v[32:35], v[132:135], v[124:127], v[32:35]
	ds_read_b128 v[154:157], v250 offset:49152
	s_waitcnt lgkmcnt(4)
	v_mfma_f32_16x16x32_bf16 v[112:115], v[136:139], v[120:123], v[112:115]
	v_mfma_f32_16x16x32_bf16 v[32:35], v[136:139], v[128:131], v[32:35]
	ds_read_b128 v[132:135], v251 offset:49152
	s_waitcnt lgkmcnt(4)
	v_mfma_f32_16x16x32_bf16 v[108:111], v[140:143], v[116:119], v[108:111]
	v_mfma_f32_16x16x32_bf16 v[28:31], v[140:143], v[124:127], v[28:31]
	ds_read_b128 v[136:139], v203 offset:49152
	s_waitcnt lgkmcnt(4)
	v_mfma_f32_16x16x32_bf16 v[108:111], v[144:147], v[120:123], v[108:111]
	v_mfma_f32_16x16x32_bf16 v[28:31], v[144:147], v[128:131], v[28:31]
	ds_read_b128 v[140:143], v219 offset:49152
	s_waitcnt lgkmcnt(4)
	v_mfma_f32_16x16x32_bf16 v[104:107], v[150:153], v[116:119], v[104:107]
	v_mfma_f32_16x16x32_bf16 v[24:27], v[150:153], v[124:127], v[24:27]
	ds_read_b128 v[144:147], v220 offset:49152
	s_waitcnt lgkmcnt(4)
	v_mfma_f32_16x16x32_bf16 v[104:107], v[154:157], v[120:123], v[104:107]
	v_mfma_f32_16x16x32_bf16 v[24:27], v[154:157], v[128:131], v[24:27]
	ds_read_b128 v[150:153], v221 offset:49152
	s_waitcnt lgkmcnt(4)
	v_mfma_f32_16x16x32_bf16 v[100:103], v[132:135], v[116:119], v[100:103]
	v_mfma_f32_16x16x32_bf16 v[20:23], v[132:135], v[124:127], v[20:23]
	ds_read_b128 v[154:157], v222 offset:49152
	s_waitcnt lgkmcnt(4)
	v_mfma_f32_16x16x32_bf16 v[100:103], v[136:139], v[120:123], v[100:103]
	v_mfma_f32_16x16x32_bf16 v[20:23], v[136:139], v[128:131], v[20:23]
	ds_read_b128 v[132:135], v223 offset:49152
	s_waitcnt lgkmcnt(4)
	v_mfma_f32_16x16x32_bf16 v[96:99], v[140:143], v[116:119], v[96:99]
	v_mfma_f32_16x16x32_bf16 v[16:19], v[140:143], v[124:127], v[16:19]
	ds_read_b128 v[136:139], v224 offset:49152
	s_waitcnt lgkmcnt(4)
	v_mfma_f32_16x16x32_bf16 v[96:99], v[144:147], v[120:123], v[96:99]
	v_mfma_f32_16x16x32_bf16 v[16:19], v[144:147], v[128:131], v[16:19]
	ds_read_b128 v[140:143], v225 offset:49152
	s_waitcnt lgkmcnt(4)
	v_mfma_f32_16x16x32_bf16 v[92:95], v[150:153], v[116:119], v[92:95]
	v_mfma_f32_16x16x32_bf16 v[12:15], v[150:153], v[124:127], v[12:15]
	ds_read_b128 v[144:147], v226 offset:49152
	s_waitcnt lgkmcnt(4)
	v_mfma_f32_16x16x32_bf16 v[92:95], v[154:157], v[120:123], v[92:95]
	v_mfma_f32_16x16x32_bf16 v[12:15], v[154:157], v[128:131], v[12:15]
	s_waitcnt lgkmcnt(3)
	v_mfma_f32_16x16x32_bf16 v[88:91], v[132:135], v[116:119], v[88:91]
	v_mfma_f32_16x16x32_bf16 v[8:11], v[132:135], v[124:127], v[8:11]
	s_waitcnt lgkmcnt(2)
	v_mfma_f32_16x16x32_bf16 v[88:91], v[136:139], v[120:123], v[88:91]
	v_mfma_f32_16x16x32_bf16 v[8:11], v[136:139], v[128:131], v[8:11]
	s_waitcnt lgkmcnt(1)
	v_mfma_f32_16x16x32_bf16 v[84:87], v[140:143], v[116:119], v[84:87]
	v_mfma_f32_16x16x32_bf16 v[4:7], v[140:143], v[124:127], v[4:7]
	s_waitcnt lgkmcnt(0)
	v_mfma_f32_16x16x32_bf16 v[84:87], v[144:147], v[120:123], v[84:87]
	v_mfma_f32_16x16x32_bf16 v[4:7], v[144:147], v[128:131], v[4:7]

; __device__ __forceinline__ void rwkv_scan2_item(const Params& p, int item, char* ldsraw) {
;     ...
;         for (int q = 0; q < 16; q++) {
;           const f32x4 cw = nw, ckk = nkk, ckka = nkka, ck = nk; const float cvA = nvA, cvB = nvB;
;           if (q < 15) R_LOAD(q + 1)
;           __builtin_amdgcn_sched_barrier(0);
;           float mA0 = mul_s(a0, ckk.x), mA1 = mul_s(a2, ckk.z), mB0 = mul_s(b0, ckk.x), mB1 = mul_s(b2, ckk.z);
;           mA0 = fma_s(a1, ckk.y, mA0); mA1 = fma_s(a3, ckk.w, mA1); mB0 = fma_s(b1, ckk.y, mB0); mB1 = fma_s(b3, ckk.w, mB1);
;           float psA = add_s(mA0, mA1), psB = add_s(mB0, mB1);
;           psA = row16_sum(psA); psB = row16_sum(psB);
;           { const float t0 = fnma_s(psA, ckka.x, mul_s(cvA, ck.x)), t1 = fnma_s(psA, ckka.y, mul_s(cvA, ck.y));
;             const float t2 = fnma_s(psA, ckka.z, mul_s(cvA, ck.z)), t3 = fnma_s(psA, ckka.w, mul_s(cvA, ck.w));
;             a0 = fma_s(a0, cw.x, t0); a1 = fma_s(a1, cw.y, t1); a2 = fma_s(a2, cw.z, t2); a3 = fma_s(a3, cw.w, t3); }
;           { const float t0 = fnma_s(psB, ckka.x, mul_s(cvB, ck.x)), t1 = fnma_s(psB, ckka.y, mul_s(cvB, ck.y));
;             const float t2 = fnma_s(psB, ckka.z, mul_s(cvB, ck.z)), t3 = fnma_s(psB, ckka.w, mul_s(cvB, ck.w));
;             b0 = fma_s(b0, cw.x, t0); b1 = fma_s(b1, cw.y, t1); b2 = fma_s(b2, cw.z, t2); b3 = fma_s(b3, cw.w, t3); }
;           sakA = sel_eq(sakA, psA, jl, q); sakB = sel_eq(sakB, psB, jl, q);
;         }
;     ...
;         SA[(c & 1) * 256 + jl * 16 + row8] = sakA; SA[(c & 1) * 256 + jl * 16 + 8 + row8] = sakB;
;       }
;     } else {
;       if (c >= 1) {
;         const float* d = buf + bprev * CH + jl * 4;
;         const float* dvp = buf + bprev * CH + 320 + row8;
;         const float* dcp = buf + bprev * CH + 336;
;         const float* sap = SA + ((c - 1) & 1) * 256 + row8;
;         f32x4 nw, nkka, nk, nwr; float nvA, nvB, nsA, nsB; f32x2 ncc;
;     ...
;         Y_LOAD(0)
;         float ykA = 0.f, ykB = 0.f;
; #pragma unroll
;         for (int q = 0; q < 16; q++) {
;           const f32x4 cw = nw, ckka = nkka, ck = nk, cwr = nwr; const float cvA = nvA, cvB = nvB, psA = nsA, psB = nsB; const f32x2 ccc = ncc;
;           if (q < 15) Y_LOAD(q + 1)
;           __builtin_amdgcn_sched_barrier(0);
;           float nA0 = mul_s(a0, cwr.x), nA1 = mul_s(a2, cwr.z), nB0 = mul_s(b0, cwr.x), nB1 = mul_s(b2, cwr.z);
.Lsc_loop:
	global_load_dwordx4 v[20:23], v12, s[24:25]
	global_load_dwordx2 v[24:25], v13, s[26:27]
	global_load_dwordx2 v[26:27], v13, s[26:27] offset:128
	global_load_dwordx2 v[28:29], v13, s[26:27] offset:256
	global_load_dwordx2 v[30:31], v13, s[26:27] offset:384
	global_load_ushort v32, v14, s[26:27]
	global_load_dwordx2 v[34:35], v15, s[28:29]
	ds_read_b128 v[44:47], v0 offset:256
	ds_read_b128 v[48:51], v0 offset:512
	ds_read_b128 v[56:59], v0 offset:1024
	ds_read_b128 v[40:43], v0 offset:0
	ds_read_b128 v[52:55], v0 offset:768
	ds_read_b128 v[80:83], v1 offset:0
	ds_read_b128 v[64:67], v0 offset:1536
	ds_read_b128 v[68:71], v0 offset:1792
	ds_read_b128 v[76:79], v0 offset:2304
	ds_read_b128 v[60:63], v0 offset:1280
	ds_read_b128 v[72:75], v0 offset:2048
	s_waitcnt lgkmcnt(9)
	v_pk_mul_f32 v[88:89], v[4:5], v[44:45] op_sel_hi:[0,1]
	v_pk_mul_f32 v[90:91], v[6:7], v[48:49] op_sel_hi:[0,1]
	v_pk_fma_f32 v[88:89], v[4:5], v[46:47], v[88:89] op_sel:[1,0,0] op_sel_hi:[1,1,1]
	v_pk_fma_f32 v[90:91], v[6:7], v[50:51], v[90:91] op_sel:[1,0,0] op_sel_hi:[1,1,1]
	v_pk_add_f32 v[100:101], v[88:89], v[90:91]
	s_waitcnt lgkmcnt(5)
	v_pk_mul_f32 v[96:97], v[80:81], v[56:57] op_sel:[0,0] op_sel_hi:[0,1]
	v_pk_mul_f32 v[98:99], v[80:81], v[58:59] op_sel:[0,0] op_sel_hi:[0,1]
	v_add_f32_dpp v93, v100, v100 quad_perm:[1,0,3,2] row_mask:0xf bank_mask:0xf
	v_pk_fma_f32 v[96:97], v[4:5], v[40:41], v[96:97]
	v_pk_fma_f32 v[98:99], v[6:7], v[42:43], v[98:99]
	v_add_f32_dpp v92, v93, v93 quad_perm:[2,3,0,1] row_mask:0xf bank_mask:0xf
	ds_read_b128 v[142:145], v0 offset:2816
	ds_read_b128 v[146:149], v0 offset:3072
	v_add_f32_dpp v93, v92, v92 row_ror:4 row_mask:0xf bank_mask:0xf
	ds_read_b128 v[154:157], v0 offset:3584
	ds_read_b128 v[138:141], v0 offset:2560
	v_add_f32_dpp v94, v93, v93 row_ror:8 row_mask:0xf bank_mask:0xf
	v_add_f32_dpp v108, v93, v93 row_ror:8 row_mask:0xf bank_mask:0x1
	ds_read_b128 v[150:153], v0 offset:3328
	v_pk_fma_f32 v[4:5], v[94:95], v[52:53], v[96:97] op_sel_hi:[0,1,1] neg_lo:[1,0,0] neg_hi:[1,0,0]
	v_pk_fma_f32 v[6:7], v[94:95], v[54:55], v[98:99] op_sel_hi:[0,1,1] neg_lo:[1,0,0] neg_hi:[1,0,0]
	s_waitcnt lgkmcnt(8)
	v_pk_mul_f32 v[88:89], v[4:5], v[64:65] op_sel_hi:[0,1]
	v_pk_mul_f32 v[90:91], v[6:7], v[68:69] op_sel_hi:[0,1]
	v_pk_fma_f32 v[88:89], v[4:5], v[66:67], v[88:89] op_sel:[1,0,0] op_sel_hi:[1,1,1]
	v_pk_fma_f32 v[90:91], v[6:7], v[70:71], v[90:91] op_sel:[1,0,0] op_sel_hi:[1,1,1]
	v_pk_add_f32 v[102:103], v[88:89], v[90:91]
	s_waitcnt lgkmcnt(7)
	v_pk_mul_f32 v[96:97], v[80:81], v[76:77] op_sel:[1,0] op_sel_hi:[1,1]
	v_pk_mul_f32 v[98:99], v[80:81], v[78:79] op_sel:[1,0] op_sel_hi:[1,1]
	v_add_f32_dpp v93, v102, v102 quad_perm:[1,0,3,2] row_mask:0xf bank_mask:0xf
	s_waitcnt lgkmcnt(6)
	v_pk_fma_f32 v[96:97], v[4:5], v[60:61], v[96:97]
	v_pk_fma_f32 v[98:99], v[6:7], v[62:63], v[98:99]
	v_add_f32_dpp v92, v93, v93 quad_perm:[2,3,0,1] row_mask:0xf bank_mask:0xf
	ds_read_b128 v[44:47], v0 offset:4096
	ds_read_b128 v[48:51], v0 offset:4352
	v_add_f32_dpp v93, v92, v92 row_ror:4 row_mask:0xf bank_mask:0xf
	ds_read_b128 v[56:59], v0 offset:4864
	ds_read_b128 v[40:43], v0 offset:3840
	v_add_f32_dpp v94, v93, v93 row_ror:8 row_mask:0xf bank_mask:0xf
	v_add_f32_dpp v108, v93, v93 row_ror:8 row_mask:0xf bank_mask:0x4
	ds_read_b128 v[52:55], v0 offset:4608
	s_waitcnt lgkmcnt(10)
	v_pk_fma_f32 v[4:5], v[94:95], v[72:73], v[96:97] op_sel_hi:[0,1,1] neg_lo:[1,0,0] neg_hi:[1,0,0]
	v_pk_fma_f32 v[6:7], v[94:95], v[74:75], v[98:99] op_sel_hi:[0,1,1] neg_lo:[1,0,0] neg_hi:[1,0,0]
	ds_read_b128 v[84:87], v1 offset:16
	v_add_f32_dpp v101, v101, v101 row_ror:8 row_mask:0xf bank_mask:0x3
	s_nop 1
	v_add_f32_dpp v101, v103, v103 row_ror:8 row_mask:0xf bank_mask:0xc
	s_waitcnt lgkmcnt(9)
	v_pk_mul_f32 v[88:89], v[4:5], v[142:143] op_sel_hi:[0,1]
	v_pk_mul_f32 v[90:91], v[6:7], v[146:147] op_sel_hi:[0,1]
	v_pk_fma_f32 v[88:89], v[4:5], v[144:145], v[88:89] op_sel:[1,0,0] op_sel_hi:[1,1,1]
	v_pk_fma_f32 v[90:91], v[6:7], v[148:149], v[90:91] op_sel:[1,0,0] op_sel_hi:[1,1,1]
	v_pk_add_f32 v[104:105], v[88:89], v[90:91]
	s_waitcnt lgkmcnt(8)
	v_pk_mul_f32 v[96:97], v[82:83], v[154:155] op_sel:[0,0] op_sel_hi:[0,1]
	v_pk_mul_f32 v[98:99], v[82:83], v[156:157] op_sel:[0,0] op_sel_hi:[0,1]
	v_add_f32_dpp v93, v104, v104 quad_perm:[1,0,3,2] row_mask:0xf bank_mask:0xf
	s_waitcnt lgkmcnt(7)
	v_pk_fma_f32 v[96:97], v[4:5], v[138:139], v[96:97]
	v_pk_fma_f32 v[98:99], v[6:7], v[140:141], v[98:99]
	v_add_f32_dpp v92, v93, v93 quad_perm:[2,3,0,1] row_mask:0xf bank_mask:0xf
	ds_read_b128 v[64:67], v0 offset:5376
	ds_read_b128 v[68:71], v0 offset:5632
	v_add_f32_dpp v93, v92, v92 row_ror:4 row_mask:0xf bank_mask:0xf
	ds_read_b128 v[76:79], v0 offset:6144
	ds_read_b128 v[60:63], v0 offset:5120
	v_add_f32_dpp v94, v93, v93 row_ror:8 row_mask:0xf bank_mask:0xf
	v_add_f32_dpp v108, v93, v93 row_ror:8 row_mask:0xf bank_mask:0x2
	ds_read_b128 v[72:75], v0 offset:5888
	s_waitcnt lgkmcnt(11)
	v_pk_fma_f32 v[4:5], v[94:95], v[150:151], v[96:97] op_sel_hi:[0,1,1] neg_lo:[1,0,0] neg_hi:[1,0,0]
	v_pk_fma_f32 v[6:7], v[94:95], v[152:153], v[98:99] op_sel_hi:[0,1,1] neg_lo:[1,0,0] neg_hi:[1,0,0]
	s_waitcnt lgkmcnt(9)
	v_pk_mul_f32 v[88:89], v[4:5], v[44:45] op_sel_hi:[0,1]
	v_pk_mul_f32 v[90:91], v[6:7], v[48:49] op_sel_hi:[0,1]
	v_pk_fma_f32 v[88:89], v[4:5], v[46:47], v[88:89] op_sel:[1,0,0] op_sel_hi:[1,1,1]
	v_pk_fma_f32 v[90:91], v[6:7], v[50:51], v[90:91] op_sel:[1,0,0] op_sel_hi:[1,1,1]
	v_pk_add_f32 v[132:133], v[88:89], v[90:91]
	s_waitcnt lgkmcnt(8)
; __device__ __forceinline__ void rwkv_scan2_item(const Params& p, int item, char* ldsraw) {
;     ...
;         for (int q = 0; q < 16; q++) {
;           const f32x4 cw = nw, ckk = nkk, ckka = nkka, ck = nk; const float cvA = nvA, cvB = nvB;
;           if (q < 15) R_LOAD(q + 1)
;           __builtin_amdgcn_sched_barrier(0);
;           float mA0 = mul_s(a0, ckk.x), mA1 = mul_s(a2, ckk.z), mB0 = mul_s(b0, ckk.x), mB1 = mul_s(b2, ckk.z);
;           mA0 = fma_s(a1, ckk.y, mA0); mA1 = fma_s(a3, ckk.w, mA1); mB0 = fma_s(b1, ckk.y, mB0); mB1 = fma_s(b3, ckk.w, mB1);
;           float psA = add_s(mA0, mA1), psB = add_s(mB0, mB1);
;           psA = row16_sum(psA); psB = row16_sum(psB);
;           { const float t0 = fnma_s(psA, ckka.x, mul_s(cvA, ck.x)), t1 = fnma_s(psA, ckka.y, mul_s(cvA, ck.y));
;             const float t2 = fnma_s(psA, ckka.z, mul_s(cvA, ck.z)), t3 = fnma_s(psA, ckka.w, mul_s(cvA, ck.w));
;             a0 = fma_s(a0, cw.x, t0); a1 = fma_s(a1, cw.y, t1); a2 = fma_s(a2, cw.z, t2); a3 = fma_s(a3, cw.w, t3); }
;           { const float t0 = fnma_s(psB, ckka.x, mul_s(cvB, ck.x)), t1 = fnma_s(psB, ckka.y, mul_s(cvB, ck.y));
;             const float t2 = fnma_s(psB, ckka.z, mul_s(cvB, ck.z)), t3 = fnma_s(psB, ckka.w, mul_s(cvB, ck.w));
;             b0 = fma_s(b0, cw.x, t0); b1 = fma_s(b1, cw.y, t1); b2 = fma_s(b2, cw.z, t2); b3 = fma_s(b3, cw.w, t3); }
;           sakA = sel_eq(sakA, psA, jl, q); sakB = sel_eq(sakB, psB, jl, q);
;         }
;     ...
;         SA[(c & 1) * 256 + jl * 16 + row8] = sakA; SA[(c & 1) * 256 + jl * 16 + 8 + row8] = sakB;
;       }
;     } else {
;       if (c >= 1) {
;         const float* d = buf + bprev * CH + jl * 4;
;         const float* dvp = buf + bprev * CH + 320 + row8;
;         const float* dcp = buf + bprev * CH + 336;
;         const float* sap = SA + ((c - 1) & 1) * 256 + row8;
;         f32x4 nw, nkka, nk, nwr; float nvA, nvB, nsA, nsB; f32x2 ncc;
;     ...
;         Y_LOAD(0)
;         float ykA = 0.f, ykB = 0.f;
; #pragma unroll
;         for (int q = 0; q < 16; q++) {
;           const f32x4 cw = nw, ckka = nkka, ck = nk, cwr = nwr; const float cvA = nvA, cvB = nvB, psA = nsA, psB = nsB; const f32x2 ccc = ncc;
;           if (q < 15) Y_LOAD(q + 1)
;           __builtin_amdgcn_sched_barrier(0);
;           float nA0 = mul_s(a0, cwr.x), nA1 = mul_s(a2, cwr.z), nB0 = mul_s(b0, cwr.x), nB1 = mul_s(b2, cwr.z);
	v_pk_mul_f32 v[96:97], v[82:83], v[56:57] op_sel:[1,0] op_sel_hi:[1,1]
	v_pk_mul_f32 v[98:99], v[82:83], v[58:59] op_sel:[1,0] op_sel_hi:[1,1]
	v_add_f32_dpp v93, v132, v132 quad_perm:[1,0,3,2] row_mask:0xf bank_mask:0xf
	s_waitcnt lgkmcnt(7)
	v_pk_fma_f32 v[96:97], v[4:5], v[40:41], v[96:97]
	v_pk_fma_f32 v[98:99], v[6:7], v[42:43], v[98:99]
	v_add_f32_dpp v92, v93, v93 quad_perm:[2,3,0,1] row_mask:0xf bank_mask:0xf
	ds_read_b128 v[142:145], v0 offset:6656
	ds_read_b128 v[146:149], v0 offset:6912
	v_add_f32_dpp v93, v92, v92 row_ror:4 row_mask:0xf bank_mask:0xf
	ds_read_b128 v[154:157], v0 offset:7424
	ds_read_b128 v[138:141], v0 offset:6400
	v_add_f32_dpp v94, v93, v93 row_ror:8 row_mask:0xf bank_mask:0xf
	v_add_f32_dpp v108, v93, v93 row_ror:8 row_mask:0xf bank_mask:0x8
	ds_read_b128 v[150:153], v0 offset:7168
	s_waitcnt lgkmcnt(11)
	v_pk_fma_f32 v[4:5], v[94:95], v[52:53], v[96:97] op_sel_hi:[0,1,1] neg_lo:[1,0,0] neg_hi:[1,0,0]
	v_pk_fma_f32 v[6:7], v[94:95], v[54:55], v[98:99] op_sel_hi:[0,1,1] neg_lo:[1,0,0] neg_hi:[1,0,0]
	v_add_f32_dpp v105, v105, v105 row_ror:8 row_mask:0xf bank_mask:0x3
	s_nop 1
	v_add_f32_dpp v105, v133, v133 row_ror:8 row_mask:0xf bank_mask:0xc
	v_add_f32_dpp v101, v101, v101 row_half_mirror row_mask:0xf bank_mask:0x5
	s_nop 1
	v_add_f32_dpp v101, v105, v105 row_half_mirror row_mask:0xf bank_mask:0xa
	s_waitcnt lgkmcnt(8)
	v_pk_mul_f32 v[88:89], v[4:5], v[64:65] op_sel_hi:[0,1]
	v_pk_mul_f32 v[90:91], v[6:7], v[68:69] op_sel_hi:[0,1]
	v_pk_fma_f32 v[88:89], v[4:5], v[66:67], v[88:89] op_sel:[1,0,0] op_sel_hi:[1,1,1]
	v_pk_fma_f32 v[90:91], v[6:7], v[70:71], v[90:91] op_sel:[1,0,0] op_sel_hi:[1,1,1]
	v_pk_add_f32 v[134:135], v[88:89], v[90:91]
	s_waitcnt lgkmcnt(7)
	v_pk_mul_f32 v[96:97], v[84:85], v[76:77] op_sel:[0,0] op_sel_hi:[0,1]
	v_pk_mul_f32 v[98:99], v[84:85], v[78:79] op_sel:[0,0] op_sel_hi:[0,1]
	v_add_f32_dpp v93, v134, v134 quad_perm:[1,0,3,2] row_mask:0xf bank_mask:0xf
	s_waitcnt lgkmcnt(6)
	v_pk_fma_f32 v[96:97], v[4:5], v[60:61], v[96:97]
	v_pk_fma_f32 v[98:99], v[6:7], v[62:63], v[98:99]
	v_add_f32_dpp v92, v93, v93 quad_perm:[2,3,0,1] row_mask:0xf bank_mask:0xf
	ds_read_b128 v[44:47], v0 offset:7936
	ds_read_b128 v[48:51], v0 offset:8192
	v_add_f32_dpp v93, v92, v92 row_ror:4 row_mask:0xf bank_mask:0xf
	ds_read_b128 v[56:59], v0 offset:8704
	ds_read_b128 v[40:43], v0 offset:7680
	v_add_f32_dpp v94, v93, v93 row_ror:8 row_mask:0xf bank_mask:0xf
	v_add_f32_dpp v109, v93, v93 row_ror:8 row_mask:0xf bank_mask:0x1
	ds_read_b128 v[52:55], v0 offset:8448
	s_waitcnt lgkmcnt(10)
	v_pk_fma_f32 v[4:5], v[94:95], v[72:73], v[96:97] op_sel_hi:[0,1,1] neg_lo:[1,0,0] neg_hi:[1,0,0]
	v_pk_fma_f32 v[6:7], v[94:95], v[74:75], v[98:99] op_sel_hi:[0,1,1] neg_lo:[1,0,0] neg_hi:[1,0,0]
	s_waitcnt lgkmcnt(8)
	v_pk_mul_f32 v[88:89], v[4:5], v[142:143] op_sel_hi:[0,1]
	v_pk_mul_f32 v[90:91], v[6:7], v[146:147] op_sel_hi:[0,1]
	v_pk_fma_f32 v[88:89], v[4:5], v[144:145], v[88:89] op_sel:[1,0,0] op_sel_hi:[1,1,1]
	v_pk_fma_f32 v[90:91], v[6:7], v[148:149], v[90:91] op_sel:[1,0,0] op_sel_hi:[1,1,1]
	v_pk_add_f32 v[136:137], v[88:89], v[90:91]
	s_waitcnt lgkmcnt(7)
	v_pk_mul_f32 v[96:97], v[84:85], v[154:155] op_sel:[1,0] op_sel_hi:[1,1]
	v_pk_mul_f32 v[98:99], v[84:85], v[156:157] op_sel:[1,0] op_sel_hi:[1,1]
	v_add_f32_dpp v93, v136, v136 quad_perm:[1,0,3,2] row_mask:0xf bank_mask:0xf
	s_waitcnt lgkmcnt(6)
	v_pk_fma_f32 v[96:97], v[4:5], v[138:139], v[96:97]
	v_pk_fma_f32 v[98:99], v[6:7], v[140:141], v[98:99]
	v_add_f32_dpp v92, v93, v93 quad_perm:[2,3,0,1] row_mask:0xf bank_mask:0xf
	ds_read_b128 v[64:67], v0 offset:9216
	ds_read_b128 v[68:71], v0 offset:9472
	v_add_f32_dpp v93, v92, v92 row_ror:4 row_mask:0xf bank_mask:0xf
	ds_read_b128 v[76:79], v0 offset:9984
	ds_read_b128 v[60:63], v0 offset:8960
	v_add_f32_dpp v94, v93, v93 row_ror:8 row_mask:0xf bank_mask:0xf
	v_add_f32_dpp v109, v93, v93 row_ror:8 row_mask:0xf bank_mask:0x4
	ds_read_b128 v[72:75], v0 offset:9728
	s_waitcnt lgkmcnt(10)
	v_pk_fma_f32 v[4:5], v[94:95], v[150:151], v[96:97] op_sel_hi:[0,1,1] neg_lo:[1,0,0] neg_hi:[1,0,0]
	v_pk_fma_f32 v[6:7], v[94:95], v[152:153], v[98:99] op_sel_hi:[0,1,1] neg_lo:[1,0,0] neg_hi:[1,0,0]
	ds_read_b128 v[80:83], v1 offset:32
	v_add_f32_dpp v135, v135, v135 row_ror:8 row_mask:0xf bank_mask:0x3
	s_nop 1
	v_add_f32_dpp v135, v137, v137 row_ror:8 row_mask:0xf bank_mask:0xc
	s_waitcnt lgkmcnt(9)
	v_pk_mul_f32 v[88:89], v[4:5], v[44:45] op_sel_hi:[0,1]
	v_pk_mul_f32 v[90:91], v[6:7], v[48:49] op_sel_hi:[0,1]
	v_pk_fma_f32 v[88:89], v[4:5], v[46:47], v[88:89] op_sel:[1,0,0] op_sel_hi:[1,1,1]
	v_pk_fma_f32 v[90:91], v[6:7], v[50:51], v[90:91] op_sel:[1,0,0] op_sel_hi:[1,1,1]
	v_pk_add_f32 v[102:103], v[88:89], v[90:91]
	s_waitcnt lgkmcnt(8)
	v_pk_mul_f32 v[96:97], v[86:87], v[56:57] op_sel:[0,0] op_sel_hi:[0,1]
	v_pk_mul_f32 v[98:99], v[86:87], v[58:59] op_sel:[0,0] op_sel_hi:[0,1]
	v_add_f32_dpp v93, v102, v102 quad_perm:[1,0,3,2] row_mask:0xf bank_mask:0xf
	s_waitcnt lgkmcnt(7)
	v_pk_fma_f32 v[96:97], v[4:5], v[40:41], v[96:97]
	v_pk_fma_f32 v[98:99], v[6:7], v[42:43], v[98:99]
	v_add_f32_dpp v92, v93, v93 quad_perm:[2,3,0,1] row_mask:0xf bank_mask:0xf
	ds_read_b128 v[142:145], v0 offset:10496
	ds_read_b128 v[146:149], v0 offset:10752
	v_add_f32_dpp v93, v92, v92 row_ror:4 row_mask:0xf bank_mask:0xf
	ds_read_b128 v[154:157], v0 offset:11264
	ds_read_b128 v[138:141], v0 offset:10240
	v_add_f32_dpp v94, v93, v93 row_ror:8 row_mask:0xf bank_mask:0xf
	v_add_f32_dpp v109, v93, v93 row_ror:8 row_mask:0xf bank_mask:0x2
	ds_read_b128 v[150:153], v0 offset:11008
	s_waitcnt lgkmcnt(11)
; __device__ __forceinline__ void rwkv_scan2_item(const Params& p, int item, char* ldsraw) {
;     ...
;         for (int q = 0; q < 16; q++) {
;           const f32x4 cw = nw, ckk = nkk, ckka = nkka, ck = nk; const float cvA = nvA, cvB = nvB;
;           if (q < 15) R_LOAD(q + 1)
;           __builtin_amdgcn_sched_barrier(0);
;           float mA0 = mul_s(a0, ckk.x), mA1 = mul_s(a2, ckk.z), mB0 = mul_s(b0, ckk.x), mB1 = mul_s(b2, ckk.z);
;           mA0 = fma_s(a1, ckk.y, mA0); mA1 = fma_s(a3, ckk.w, mA1); mB0 = fma_s(b1, ckk.y, mB0); mB1 = fma_s(b3, ckk.w, mB1);
;           float psA = add_s(mA0, mA1), psB = add_s(mB0, mB1);
;           psA = row16_sum(psA); psB = row16_sum(psB);
;           { const float t0 = fnma_s(psA, ckka.x, mul_s(cvA, ck.x)), t1 = fnma_s(psA, ckka.y, mul_s(cvA, ck.y));
;             const float t2 = fnma_s(psA, ckka.z, mul_s(cvA, ck.z)), t3 = fnma_s(psA, ckka.w, mul_s(cvA, ck.w));
;             a0 = fma_s(a0, cw.x, t0); a1 = fma_s(a1, cw.y, t1); a2 = fma_s(a2, cw.z, t2); a3 = fma_s(a3, cw.w, t3); }
;           { const float t0 = fnma_s(psB, ckka.x, mul_s(cvB, ck.x)), t1 = fnma_s(psB, ckka.y, mul_s(cvB, ck.y));
;             const float t2 = fnma_s(psB, ckka.z, mul_s(cvB, ck.z)), t3 = fnma_s(psB, ckka.w, mul_s(cvB, ck.w));
;             b0 = fma_s(b0, cw.x, t0); b1 = fma_s(b1, cw.y, t1); b2 = fma_s(b2, cw.z, t2); b3 = fma_s(b3, cw.w, t3); }
;           sakA = sel_eq(sakA, psA, jl, q); sakB = sel_eq(sakB, psB, jl, q);
;         }
;     ...
;         SA[(c & 1) * 256 + jl * 16 + row8] = sakA; SA[(c & 1) * 256 + jl * 16 + 8 + row8] = sakB;
;       }
;     } else {
;       if (c >= 1) {
;         const float* d = buf + bprev * CH + jl * 4;
;         const float* dvp = buf + bprev * CH + 320 + row8;
;         const float* dcp = buf + bprev * CH + 336;
;         const float* sap = SA + ((c - 1) & 1) * 256 + row8;
;         f32x4 nw, nkka, nk, nwr; float nvA, nvB, nsA, nsB; f32x2 ncc;
;     ...
;         Y_LOAD(0)
;         float ykA = 0.f, ykB = 0.f;
; #pragma unroll
;         for (int q = 0; q < 16; q++) {
;           const f32x4 cw = nw, ckka = nkka, ck = nk, cwr = nwr; const float cvA = nvA, cvB = nvB, psA = nsA, psB = nsB; const f32x2 ccc = ncc;
;           if (q < 15) Y_LOAD(q + 1)
;           __builtin_amdgcn_sched_barrier(0);
;           float nA0 = mul_s(a0, cwr.x), nA1 = mul_s(a2, cwr.z), nB0 = mul_s(b0, cwr.x), nB1 = mul_s(b2, cwr.z);
	v_pk_fma_f32 v[4:5], v[94:95], v[52:53], v[96:97] op_sel_hi:[0,1,1] neg_lo:[1,0,0] neg_hi:[1,0,0]
	v_pk_fma_f32 v[6:7], v[94:95], v[54:55], v[98:99] op_sel_hi:[0,1,1] neg_lo:[1,0,0] neg_hi:[1,0,0]
	s_waitcnt lgkmcnt(9)
	v_pk_mul_f32 v[88:89], v[4:5], v[64:65] op_sel_hi:[0,1]
	v_pk_mul_f32 v[90:91], v[6:7], v[68:69] op_sel_hi:[0,1]
	v_pk_fma_f32 v[88:89], v[4:5], v[66:67], v[88:89] op_sel:[1,0,0] op_sel_hi:[1,1,1]
	v_pk_fma_f32 v[90:91], v[6:7], v[70:71], v[90:91] op_sel:[1,0,0] op_sel_hi:[1,1,1]
	v_pk_add_f32 v[132:133], v[88:89], v[90:91]
	s_waitcnt lgkmcnt(8)
	v_pk_mul_f32 v[96:97], v[86:87], v[76:77] op_sel:[1,0] op_sel_hi:[1,1]
	v_pk_mul_f32 v[98:99], v[86:87], v[78:79] op_sel:[1,0] op_sel_hi:[1,1]
	v_add_f32_dpp v93, v132, v132 quad_perm:[1,0,3,2] row_mask:0xf bank_mask:0xf
	s_waitcnt lgkmcnt(7)
	v_pk_fma_f32 v[96:97], v[4:5], v[60:61], v[96:97]
	v_pk_fma_f32 v[98:99], v[6:7], v[62:63], v[98:99]
	v_add_f32_dpp v92, v93, v93 quad_perm:[2,3,0,1] row_mask:0xf bank_mask:0xf
	ds_read_b128 v[44:47], v0 offset:11776
	ds_read_b128 v[48:51], v0 offset:12032
	v_add_f32_dpp v93, v92, v92 row_ror:4 row_mask:0xf bank_mask:0xf
	ds_read_b128 v[56:59], v0 offset:12544
	ds_read_b128 v[40:43], v0 offset:11520
	v_add_f32_dpp v94, v93, v93 row_ror:8 row_mask:0xf bank_mask:0xf
	v_add_f32_dpp v109, v93, v93 row_ror:8 row_mask:0xf bank_mask:0x8
	ds_read_b128 v[52:55], v0 offset:12288
	s_waitcnt lgkmcnt(11)
	v_pk_fma_f32 v[4:5], v[94:95], v[72:73], v[96:97] op_sel_hi:[0,1,1] neg_lo:[1,0,0] neg_hi:[1,0,0]
	v_pk_fma_f32 v[6:7], v[94:95], v[74:75], v[98:99] op_sel_hi:[0,1,1] neg_lo:[1,0,0] neg_hi:[1,0,0]
	v_add_f32_dpp v103, v103, v103 row_ror:8 row_mask:0xf bank_mask:0x3
	s_nop 1
	v_add_f32_dpp v103, v133, v133 row_ror:8 row_mask:0xf bank_mask:0xc
	v_add_f32_dpp v135, v135, v135 row_half_mirror row_mask:0xf bank_mask:0x5
	s_nop 1
	v_add_f32_dpp v135, v103, v103 row_half_mirror row_mask:0xf bank_mask:0xa
	v_cndmask_b32_e64 v106, v135, v101, s[36:37]
	v_cndmask_b32_e64 v107, v101, v135, s[36:37]
	s_nop 1
	v_add_f32_dpp v101, v106, v107 quad_perm:[2,3,0,1] row_mask:0xf bank_mask:0xf
	s_waitcnt lgkmcnt(8)
	v_pk_mul_f32 v[88:89], v[4:5], v[142:143] op_sel_hi:[0,1]
	v_pk_mul_f32 v[90:91], v[6:7], v[146:147] op_sel_hi:[0,1]
	v_pk_fma_f32 v[88:89], v[4:5], v[144:145], v[88:89] op_sel:[1,0,0] op_sel_hi:[1,1,1]
	v_pk_fma_f32 v[90:91], v[6:7], v[148:149], v[90:91] op_sel:[1,0,0] op_sel_hi:[1,1,1]
	v_pk_add_f32 v[104:105], v[88:89], v[90:91]
	s_waitcnt lgkmcnt(7)
	v_pk_mul_f32 v[96:97], v[80:81], v[154:155] op_sel:[0,0] op_sel_hi:[0,1]
	v_pk_mul_f32 v[98:99], v[80:81], v[156:157] op_sel:[0,0] op_sel_hi:[0,1]
	v_add_f32_dpp v93, v104, v104 quad_perm:[1,0,3,2] row_mask:0xf bank_mask:0xf
	s_waitcnt lgkmcnt(6)
	v_pk_fma_f32 v[96:97], v[4:5], v[138:139], v[96:97]
	v_pk_fma_f32 v[98:99], v[6:7], v[140:141], v[98:99]
	v_add_f32_dpp v92, v93, v93 quad_perm:[2,3,0,1] row_mask:0xf bank_mask:0xf
	ds_read_b128 v[64:67], v0 offset:13056
	ds_read_b128 v[68:71], v0 offset:13312
	v_add_f32_dpp v93, v92, v92 row_ror:4 row_mask:0xf bank_mask:0xf
	ds_read_b128 v[76:79], v0 offset:13824
	ds_read_b128 v[60:63], v0 offset:12800
	v_add_f32_dpp v94, v93, v93 row_ror:8 row_mask:0xf bank_mask:0xf
	v_add_f32_dpp v110, v93, v93 row_ror:8 row_mask:0xf bank_mask:0x1
	ds_read_b128 v[72:75], v0 offset:13568
	s_waitcnt lgkmcnt(10)
	v_pk_fma_f32 v[4:5], v[94:95], v[150:151], v[96:97] op_sel_hi:[0,1,1] neg_lo:[1,0,0] neg_hi:[1,0,0]
	v_pk_fma_f32 v[6:7], v[94:95], v[152:153], v[98:99] op_sel_hi:[0,1,1] neg_lo:[1,0,0] neg_hi:[1,0,0]
	s_waitcnt lgkmcnt(8)
	v_pk_mul_f32 v[88:89], v[4:5], v[44:45] op_sel_hi:[0,1]
	v_pk_mul_f32 v[90:91], v[6:7], v[48:49] op_sel_hi:[0,1]
	v_pk_fma_f32 v[88:89], v[4:5], v[46:47], v[88:89] op_sel:[1,0,0] op_sel_hi:[1,1,1]
	v_pk_fma_f32 v[90:91], v[6:7], v[50:51], v[90:91] op_sel:[1,0,0] op_sel_hi:[1,1,1]
	v_pk_add_f32 v[136:137], v[88:89], v[90:91]
	s_waitcnt lgkmcnt(7)
	v_pk_mul_f32 v[96:97], v[80:81], v[56:57] op_sel:[1,0] op_sel_hi:[1,1]
	v_pk_mul_f32 v[98:99], v[80:81], v[58:59] op_sel:[1,0] op_sel_hi:[1,1]
	v_add_f32_dpp v93, v136, v136 quad_perm:[1,0,3,2] row_mask:0xf bank_mask:0xf
	s_waitcnt lgkmcnt(6)
	v_pk_fma_f32 v[96:97], v[4:5], v[40:41], v[96:97]
	v_pk_fma_f32 v[98:99], v[6:7], v[42:43], v[98:99]
	v_add_f32_dpp v92, v93, v93 quad_perm:[2,3,0,1] row_mask:0xf bank_mask:0xf
	ds_read_b128 v[142:145], v0 offset:14336
	ds_read_b128 v[146:149], v0 offset:14592
	v_add_f32_dpp v93, v92, v92 row_ror:4 row_mask:0xf bank_mask:0xf
	ds_read_b128 v[154:157], v0 offset:15104
	ds_read_b128 v[138:141], v0 offset:14080
	v_add_f32_dpp v94, v93, v93 row_ror:8 row_mask:0xf bank_mask:0xf
	v_add_f32_dpp v110, v93, v93 row_ror:8 row_mask:0xf bank_mask:0x4
	ds_read_b128 v[150:153], v0 offset:14848
	s_waitcnt lgkmcnt(10)
	v_pk_fma_f32 v[4:5], v[94:95], v[52:53], v[96:97] op_sel_hi:[0,1,1] neg_lo:[1,0,0] neg_hi:[1,0,0]
	v_pk_fma_f32 v[6:7], v[94:95], v[54:55], v[98:99] op_sel_hi:[0,1,1] neg_lo:[1,0,0] neg_hi:[1,0,0]
	ds_read_b128 v[84:87], v1 offset:48
	v_add_f32_dpp v105, v105, v105 row_ror:8 row_mask:0xf bank_mask:0x3
	s_nop 1
	v_add_f32_dpp v105, v137, v137 row_ror:8 row_mask:0xf bank_mask:0xc
	s_waitcnt lgkmcnt(9)
	v_pk_mul_f32 v[88:89], v[4:5], v[64:65] op_sel_hi:[0,1]
	v_pk_mul_f32 v[90:91], v[6:7], v[68:69] op_sel_hi:[0,1]
	v_pk_fma_f32 v[88:89], v[4:5], v[66:67], v[88:89] op_sel:[1,0,0] op_sel_hi:[1,1,1]
	v_pk_fma_f32 v[90:91], v[6:7], v[70:71], v[90:91] op_sel:[1,0,0] op_sel_hi:[1,1,1]
	v_pk_add_f32 v[132:133], v[88:89], v[90:91]
	s_waitcnt lgkmcnt(8)
	v_pk_mul_f32 v[96:97], v[82:83], v[76:77] op_sel:[0,0] op_sel_hi:[0,1]
	v_pk_mul_f32 v[98:99], v[82:83], v[78:79] op_sel:[0,0] op_sel_hi:[0,1]
	v_add_f32_dpp v93, v132, v132 quad_perm:[1,0,3,2] row_mask:0xf bank_mask:0xf
	s_waitcnt lgkmcnt(7)
; __device__ __forceinline__ void rwkv_scan2_item(const Params& p, int item, char* ldsraw) {
;     ...
;         for (int q = 0; q < 16; q++) {
;           const f32x4 cw = nw, ckk = nkk, ckka = nkka, ck = nk; const float cvA = nvA, cvB = nvB;
;           if (q < 15) R_LOAD(q + 1)
;           __builtin_amdgcn_sched_barrier(0);
;           float mA0 = mul_s(a0, ckk.x), mA1 = mul_s(a2, ckk.z), mB0 = mul_s(b0, ckk.x), mB1 = mul_s(b2, ckk.z);
;           mA0 = fma_s(a1, ckk.y, mA0); mA1 = fma_s(a3, ckk.w, mA1); mB0 = fma_s(b1, ckk.y, mB0); mB1 = fma_s(b3, ckk.w, mB1);
;           float psA = add_s(mA0, mA1), psB = add_s(mB0, mB1);
;           psA = row16_sum(psA); psB = row16_sum(psB);
;           { const float t0 = fnma_s(psA, ckka.x, mul_s(cvA, ck.x)), t1 = fnma_s(psA, ckka.y, mul_s(cvA, ck.y));
;             const float t2 = fnma_s(psA, ckka.z, mul_s(cvA, ck.z)), t3 = fnma_s(psA, ckka.w, mul_s(cvA, ck.w));
;             a0 = fma_s(a0, cw.x, t0); a1 = fma_s(a1, cw.y, t1); a2 = fma_s(a2, cw.z, t2); a3 = fma_s(a3, cw.w, t3); }
;           { const float t0 = fnma_s(psB, ckka.x, mul_s(cvB, ck.x)), t1 = fnma_s(psB, ckka.y, mul_s(cvB, ck.y));
;             const float t2 = fnma_s(psB, ckka.z, mul_s(cvB, ck.z)), t3 = fnma_s(psB, ckka.w, mul_s(cvB, ck.w));
;             b0 = fma_s(b0, cw.x, t0); b1 = fma_s(b1, cw.y, t1); b2 = fma_s(b2, cw.z, t2); b3 = fma_s(b3, cw.w, t3); }
;           sakA = sel_eq(sakA, psA, jl, q); sakB = sel_eq(sakB, psB, jl, q);
;         }
;     ...
;         SA[(c & 1) * 256 + jl * 16 + row8] = sakA; SA[(c & 1) * 256 + jl * 16 + 8 + row8] = sakB;
;       }
;     } else {
;       if (c >= 1) {
;         const float* d = buf + bprev * CH + jl * 4;
;         const float* dvp = buf + bprev * CH + 320 + row8;
;         const float* dcp = buf + bprev * CH + 336;
;         const float* sap = SA + ((c - 1) & 1) * 256 + row8;
;         f32x4 nw, nkka, nk, nwr; float nvA, nvB, nsA, nsB; f32x2 ncc;
;     ...
;         Y_LOAD(0)
;         float ykA = 0.f, ykB = 0.f;
; #pragma unroll
;         for (int q = 0; q < 16; q++) {
;           const f32x4 cw = nw, ckka = nkka, ck = nk, cwr = nwr; const float cvA = nvA, cvB = nvB, psA = nsA, psB = nsB; const f32x2 ccc = ncc;
;           if (q < 15) Y_LOAD(q + 1)
;           __builtin_amdgcn_sched_barrier(0);
;           float nA0 = mul_s(a0, cwr.x), nA1 = mul_s(a2, cwr.z), nB0 = mul_s(b0, cwr.x), nB1 = mul_s(b2, cwr.z);
	v_pk_fma_f32 v[96:97], v[4:5], v[60:61], v[96:97]
	v_pk_fma_f32 v[98:99], v[6:7], v[62:63], v[98:99]
	v_add_f32_dpp v92, v93, v93 quad_perm:[2,3,0,1] row_mask:0xf bank_mask:0xf
	ds_read_b128 v[44:47], v0 offset:15616
	ds_read_b128 v[48:51], v0 offset:15872
	v_add_f32_dpp v93, v92, v92 row_ror:4 row_mask:0xf bank_mask:0xf
	ds_read_b128 v[56:59], v0 offset:16384
	ds_read_b128 v[40:43], v0 offset:15360
	v_add_f32_dpp v94, v93, v93 row_ror:8 row_mask:0xf bank_mask:0xf
	v_add_f32_dpp v110, v93, v93 row_ror:8 row_mask:0xf bank_mask:0x2
	ds_read_b128 v[52:55], v0 offset:16128
	s_waitcnt lgkmcnt(11)
	v_pk_fma_f32 v[4:5], v[94:95], v[72:73], v[96:97] op_sel_hi:[0,1,1] neg_lo:[1,0,0] neg_hi:[1,0,0]
	v_pk_fma_f32 v[6:7], v[94:95], v[74:75], v[98:99] op_sel_hi:[0,1,1] neg_lo:[1,0,0] neg_hi:[1,0,0]
	s_waitcnt lgkmcnt(9)
	v_pk_mul_f32 v[88:89], v[4:5], v[142:143] op_sel_hi:[0,1]
	v_pk_mul_f32 v[90:91], v[6:7], v[146:147] op_sel_hi:[0,1]
	v_pk_fma_f32 v[88:89], v[4:5], v[144:145], v[88:89] op_sel:[1,0,0] op_sel_hi:[1,1,1]
	v_pk_fma_f32 v[90:91], v[6:7], v[148:149], v[90:91] op_sel:[1,0,0] op_sel_hi:[1,1,1]
	v_pk_add_f32 v[102:103], v[88:89], v[90:91]
	s_waitcnt lgkmcnt(8)
	v_pk_mul_f32 v[96:97], v[82:83], v[154:155] op_sel:[1,0] op_sel_hi:[1,1]
	v_pk_mul_f32 v[98:99], v[82:83], v[156:157] op_sel:[1,0] op_sel_hi:[1,1]
	v_add_f32_dpp v93, v102, v102 quad_perm:[1,0,3,2] row_mask:0xf bank_mask:0xf
	s_waitcnt lgkmcnt(7)
	v_pk_fma_f32 v[96:97], v[4:5], v[138:139], v[96:97]
	v_pk_fma_f32 v[98:99], v[6:7], v[140:141], v[98:99]
	v_add_f32_dpp v92, v93, v93 quad_perm:[2,3,0,1] row_mask:0xf bank_mask:0xf
	ds_read_b128 v[64:67], v0 offset:16896
	ds_read_b128 v[68:71], v0 offset:17152
	v_add_f32_dpp v93, v92, v92 row_ror:4 row_mask:0xf bank_mask:0xf
	ds_read_b128 v[76:79], v0 offset:17664
	ds_read_b128 v[60:63], v0 offset:16640
	v_add_f32_dpp v94, v93, v93 row_ror:8 row_mask:0xf bank_mask:0xf
	v_add_f32_dpp v110, v93, v93 row_ror:8 row_mask:0xf bank_mask:0x8
	ds_read_b128 v[72:75], v0 offset:17408
	s_waitcnt lgkmcnt(11)
	v_pk_fma_f32 v[4:5], v[94:95], v[150:151], v[96:97] op_sel_hi:[0,1,1] neg_lo:[1,0,0] neg_hi:[1,0,0]
	v_pk_fma_f32 v[6:7], v[94:95], v[152:153], v[98:99] op_sel_hi:[0,1,1] neg_lo:[1,0,0] neg_hi:[1,0,0]
	v_add_f32_dpp v133, v133, v133 row_ror:8 row_mask:0xf bank_mask:0x3
	s_nop 1
	v_add_f32_dpp v133, v103, v103 row_ror:8 row_mask:0xf bank_mask:0xc
	v_add_f32_dpp v105, v105, v105 row_half_mirror row_mask:0xf bank_mask:0x5
	s_nop 1
	v_add_f32_dpp v105, v133, v133 row_half_mirror row_mask:0xf bank_mask:0xa
	s_waitcnt lgkmcnt(8)
	v_pk_mul_f32 v[88:89], v[4:5], v[44:45] op_sel_hi:[0,1]
	v_pk_mul_f32 v[90:91], v[6:7], v[48:49] op_sel_hi:[0,1]
	v_pk_fma_f32 v[88:89], v[4:5], v[46:47], v[88:89] op_sel:[1,0,0] op_sel_hi:[1,1,1]
	v_pk_fma_f32 v[90:91], v[6:7], v[50:51], v[90:91] op_sel:[1,0,0] op_sel_hi:[1,1,1]
	v_pk_add_f32 v[134:135], v[88:89], v[90:91]
	s_waitcnt lgkmcnt(7)
	v_pk_mul_f32 v[96:97], v[84:85], v[56:57] op_sel:[0,0] op_sel_hi:[0,1]
	v_pk_mul_f32 v[98:99], v[84:85], v[58:59] op_sel:[0,0] op_sel_hi:[0,1]
	v_add_f32_dpp v93, v134, v134 quad_perm:[1,0,3,2] row_mask:0xf bank_mask:0xf
	s_waitcnt lgkmcnt(6)
	v_pk_fma_f32 v[96:97], v[4:5], v[40:41], v[96:97]
	v_pk_fma_f32 v[98:99], v[6:7], v[42:43], v[98:99]
	v_add_f32_dpp v92, v93, v93 quad_perm:[2,3,0,1] row_mask:0xf bank_mask:0xf
	ds_read_b128 v[142:145], v0 offset:18176
	ds_read_b128 v[146:149], v0 offset:18432
	v_add_f32_dpp v93, v92, v92 row_ror:4 row_mask:0xf bank_mask:0xf
	ds_read_b128 v[154:157], v0 offset:18944
	ds_read_b128 v[138:141], v0 offset:17920
	v_add_f32_dpp v94, v93, v93 row_ror:8 row_mask:0xf bank_mask:0xf
	v_add_f32_dpp v111, v93, v93 row_ror:8 row_mask:0xf bank_mask:0x1
	ds_read_b128 v[150:153], v0 offset:18688
	s_waitcnt lgkmcnt(10)
	v_pk_fma_f32 v[4:5], v[94:95], v[52:53], v[96:97] op_sel_hi:[0,1,1] neg_lo:[1,0,0] neg_hi:[1,0,0]
	v_pk_fma_f32 v[6:7], v[94:95], v[54:55], v[98:99] op_sel_hi:[0,1,1] neg_lo:[1,0,0] neg_hi:[1,0,0]
	s_waitcnt lgkmcnt(8)
	v_pk_mul_f32 v[88:89], v[4:5], v[64:65] op_sel_hi:[0,1]
	v_pk_mul_f32 v[90:91], v[6:7], v[68:69] op_sel_hi:[0,1]
	v_pk_fma_f32 v[88:89], v[4:5], v[66:67], v[88:89] op_sel:[1,0,0] op_sel_hi:[1,1,1]
	v_pk_fma_f32 v[90:91], v[6:7], v[70:71], v[90:91] op_sel:[1,0,0] op_sel_hi:[1,1,1]
	v_pk_add_f32 v[136:137], v[88:89], v[90:91]
	s_waitcnt lgkmcnt(7)
	v_pk_mul_f32 v[96:97], v[84:85], v[76:77] op_sel:[1,0] op_sel_hi:[1,1]
	v_pk_mul_f32 v[98:99], v[84:85], v[78:79] op_sel:[1,0] op_sel_hi:[1,1]
	v_add_f32_dpp v93, v136, v136 quad_perm:[1,0,3,2] row_mask:0xf bank_mask:0xf
	s_waitcnt lgkmcnt(6)
	v_pk_fma_f32 v[96:97], v[4:5], v[60:61], v[96:97]
	v_pk_fma_f32 v[98:99], v[6:7], v[62:63], v[98:99]
	v_add_f32_dpp v92, v93, v93 quad_perm:[2,3,0,1] row_mask:0xf bank_mask:0xf
	ds_read_b128 v[44:47], v0 offset:19456
	ds_read_b128 v[48:51], v0 offset:19712
	v_add_f32_dpp v93, v92, v92 row_ror:4 row_mask:0xf bank_mask:0xf
	ds_read_b128 v[56:59], v0 offset:20224
	ds_read_b128 v[40:43], v0 offset:19200
	v_add_f32_dpp v94, v93, v93 row_ror:8 row_mask:0xf bank_mask:0xf
	v_add_f32_dpp v111, v93, v93 row_ror:8 row_mask:0xf bank_mask:0x4
	ds_read_b128 v[52:55], v0 offset:19968
	s_waitcnt lgkmcnt(10)
	v_pk_fma_f32 v[4:5], v[94:95], v[72:73], v[96:97] op_sel_hi:[0,1,1] neg_lo:[1,0,0] neg_hi:[1,0,0]
	v_pk_fma_f32 v[6:7], v[94:95], v[74:75], v[98:99] op_sel_hi:[0,1,1] neg_lo:[1,0,0] neg_hi:[1,0,0]
	ds_read_b32 v112, v10 offset:0
	ds_read_b64 v[114:115], v11 offset:0
	v_add_f32_dpp v135, v135, v135 row_ror:8 row_mask:0xf bank_mask:0x3
	s_nop 1
	v_add_f32_dpp v135, v137, v137 row_ror:8 row_mask:0xf bank_mask:0xc
	s_waitcnt lgkmcnt(10)
; __device__ __forceinline__ float bf2f(unsigned short b) { return __uint_as_float(((unsigned)b) << 16); }
; __device__ __forceinline__ unsigned short f2bf(float f) { unsigned r; asm("v_cvt_pk_bf16_f32 %0, %1, %1" : "=v"(r) : "v"(f)); return (unsigned short)(r & 0xffffu); }
; __device__ __forceinline__ float bflo(unsigned u) { return __uint_as_float(u << 16); }
; __device__ __forceinline__ float bfhi(unsigned u) { return __uint_as_float(u & 0xffff0000u); }
; __device__ __forceinline__ float fma_s(float a, float b, float c) { float d; asm("v_fma_f32 %0, %1, %2, %3" : "=v"(d) : "v"(a), "v"(b), "v"(c)); return d; }
; __device__ __forceinline__ float fnma_s(float a, float b, float c) { float d; asm("v_fma_f32 %0, -%1, %2, %3" : "=v"(d) : "v"(a), "v"(b), "v"(c)); return d; }
; __device__ __forceinline__ float sel_eq(float keep, float v, int a, int b) { asm("v_cmp_eq_u32 vcc, %1, %2\n\tv_cndmask_b32 %0, %0, %3, vcc" : "+v"(keep) : "v"(a), "v"(b), "v"(v) : "vcc"); return keep; }
; __device__ __forceinline__ void rwkv_scan2_item(const Params& p, int item, char* ldsraw) {
;     ...
;   auto store = [&](int bi) {
;     float* d = buf + bi * CH + st * STEP;
;     *(f32x4*)(d + part * 4) = pw;
;     *(f32x4*)(d + 64 + part * 4) = (f32x4){bflo(pkk[0]), bfhi(pkk[0]), bflo(pkk[1]), bfhi(pkk[1])};
;     *(f32x4*)(d + 128 + part * 4) = (f32x4){bflo(pkka[0]), bfhi(pkka[0]), bflo(pkka[1]), bfhi(pkka[1])};
;     *(f32x4*)(d + 192 + part * 4) = (f32x4){bflo(pk[0]), bfhi(pk[0]), bflo(pk[1]), bfhi(pk[1])};
;     *(f32x4*)(d + 256 + part * 4) = (f32x4){bflo(pwr[0]), bfhi(pwr[0]), bflo(pwr[1]), bfhi(pwr[1])};
;     d[320 + part] = ident ? 0.f : bf2f(pv);
;     if (part < 2) d[336 + part] = pc;
;   };
;     ...
;           const float yA = fnma_s(psA, ccc.x, fma_s(cvA, ccc.y, puA)), yB = fnma_s(psB, ccc.x, fma_s(cvB, ccc.y, puB));
;           ykA = sel_eq(ykA, yA, jl, q); ykB = sel_eq(ykB, yB, jl, q);
;         }
;     ...
;         yout[(size_t)(c - 1) * ystride] = f2bf(ykA); yout[(size_t)(c - 1) * ystride + 8] = f2bf(ykB);
;       }
;     }
;     if (c + 1 < 128) store(bnext);
;     bi = bnext;
;     asm volatile("s_waitcnt lgkmcnt(0)" ::: "memory"); __builtin_amdgcn_s_barrier(); asm volatile("" ::: "memory");
	v_pk_mul_f32 v[88:89], v[4:5], v[142:143] op_sel_hi:[0,1]
	v_pk_mul_f32 v[90:91], v[6:7], v[146:147] op_sel_hi:[0,1]
	v_pk_fma_f32 v[88:89], v[4:5], v[144:145], v[88:89] op_sel:[1,0,0] op_sel_hi:[1,1,1]
	v_pk_fma_f32 v[90:91], v[6:7], v[148:149], v[90:91] op_sel:[1,0,0] op_sel_hi:[1,1,1]
	v_pk_add_f32 v[102:103], v[88:89], v[90:91]
	s_waitcnt lgkmcnt(9)
	v_pk_mul_f32 v[96:97], v[86:87], v[154:155] op_sel:[0,0] op_sel_hi:[0,1]
	v_pk_mul_f32 v[98:99], v[86:87], v[156:157] op_sel:[0,0] op_sel_hi:[0,1]
	v_add_f32_dpp v93, v102, v102 quad_perm:[1,0,3,2] row_mask:0xf bank_mask:0xf
	s_waitcnt lgkmcnt(8)
	v_pk_fma_f32 v[96:97], v[4:5], v[138:139], v[96:97]
	v_pk_fma_f32 v[98:99], v[6:7], v[140:141], v[98:99]
	v_add_f32_dpp v92, v93, v93 quad_perm:[2,3,0,1] row_mask:0xf bank_mask:0xf
	s_nop 1
	v_add_f32_dpp v93, v92, v92 row_ror:4 row_mask:0xf bank_mask:0xf
	s_nop 1
	v_add_f32_dpp v94, v93, v93 row_ror:8 row_mask:0xf bank_mask:0xf
	v_add_f32_dpp v111, v93, v93 row_ror:8 row_mask:0xf bank_mask:0x2
	s_waitcnt lgkmcnt(7)
	v_pk_fma_f32 v[4:5], v[94:95], v[150:151], v[96:97] op_sel_hi:[0,1,1] neg_lo:[1,0,0] neg_hi:[1,0,0]
	v_pk_fma_f32 v[6:7], v[94:95], v[152:153], v[98:99] op_sel_hi:[0,1,1] neg_lo:[1,0,0] neg_hi:[1,0,0]
	s_waitcnt lgkmcnt(5)
	v_pk_mul_f32 v[88:89], v[4:5], v[44:45] op_sel_hi:[0,1]
	v_pk_mul_f32 v[90:91], v[6:7], v[48:49] op_sel_hi:[0,1]
	v_pk_fma_f32 v[88:89], v[4:5], v[46:47], v[88:89] op_sel:[1,0,0] op_sel_hi:[1,1,1]
	v_pk_fma_f32 v[90:91], v[6:7], v[50:51], v[90:91] op_sel:[1,0,0] op_sel_hi:[1,1,1]
	v_pk_add_f32 v[132:133], v[88:89], v[90:91]
	s_waitcnt lgkmcnt(4)
	v_pk_mul_f32 v[96:97], v[86:87], v[56:57] op_sel:[1,0] op_sel_hi:[1,1]
	v_pk_mul_f32 v[98:99], v[86:87], v[58:59] op_sel:[1,0] op_sel_hi:[1,1]
	v_add_f32_dpp v93, v132, v132 quad_perm:[1,0,3,2] row_mask:0xf bank_mask:0xf
	s_waitcnt lgkmcnt(3)
	v_pk_fma_f32 v[96:97], v[4:5], v[40:41], v[96:97]
	v_pk_fma_f32 v[98:99], v[6:7], v[42:43], v[98:99]
	v_add_f32_dpp v92, v93, v93 quad_perm:[2,3,0,1] row_mask:0xf bank_mask:0xf
	s_nop 1
	v_add_f32_dpp v93, v92, v92 row_ror:4 row_mask:0xf bank_mask:0xf
	s_nop 1
	v_add_f32_dpp v94, v93, v93 row_ror:8 row_mask:0xf bank_mask:0xf
	v_add_f32_dpp v111, v93, v93 row_ror:8 row_mask:0xf bank_mask:0x8
	s_waitcnt lgkmcnt(2)
	v_pk_fma_f32 v[4:5], v[94:95], v[52:53], v[96:97] op_sel_hi:[0,1,1] neg_lo:[1,0,0] neg_hi:[1,0,0]
	v_pk_fma_f32 v[6:7], v[94:95], v[54:55], v[98:99] op_sel_hi:[0,1,1] neg_lo:[1,0,0] neg_hi:[1,0,0]
	v_add_f32_dpp v103, v103, v103 row_ror:8 row_mask:0xf bank_mask:0x3
	s_nop 1
	v_add_f32_dpp v103, v133, v133 row_ror:8 row_mask:0xf bank_mask:0xc
	v_add_f32_dpp v135, v135, v135 row_half_mirror row_mask:0xf bank_mask:0x5
	s_nop 1
	v_add_f32_dpp v135, v103, v103 row_half_mirror row_mask:0xf bank_mask:0xa
	v_cndmask_b32_e64 v106, v135, v105, s[36:37]
	v_cndmask_b32_e64 v107, v105, v135, s[36:37]
	s_nop 1
	v_add_f32_dpp v105, v106, v107 quad_perm:[2,3,0,1] row_mask:0xf bank_mask:0xf
	v_cndmask_b32_e64 v106, v105, v101, s[34:35]
	v_cndmask_b32_e64 v107, v101, v105, s[34:35]
	s_nop 1
	v_add_f32_dpp v101, v106, v107 quad_perm:[1,0,3,2] row_mask:0xf bank_mask:0xf
	v_cndmask_b32_e64 v106, v108, v110, s[34:35]
	v_cndmask_b32_e64 v107, v109, v111, s[34:35]
	v_cndmask_b32_e64 v106, v106, v107, s[36:37]
	s_waitcnt lgkmcnt(0)
	v_fma_f32 v101, v112, v115, v101
	v_fma_f32 v101, -v106, v114, v101
	v_cvt_pk_bf16_f32 v107, v101, v101
	global_store_short v16, v107, s[30:31]
	s_waitcnt vmcnt(1)
	ds_write_b128 v2, v[20:23] offset:21632
	v_lshlrev_b32_e32 v36, 16, v24
	v_lshlrev_b32_e32 v37, 16, v30
	v_and_b32_e32 v38, 0xffff0000, v24
	v_and_b32_e32 v39, 0xffff0000, v30
	ds_write_b128 v2, v[36:39] offset:21888
	v_lshlrev_b32_e32 v40, 16, v25
	v_lshlrev_b32_e32 v41, 16, v31
	v_and_b32_e32 v42, 0xffff0000, v25
	v_and_b32_e32 v43, 0xffff0000, v31
	ds_write_b128 v2, v[40:43] offset:22144
	v_lshlrev_b32_e32 v44, 16, v26
	v_and_b32_e32 v45, 0xffff0000, v26
	v_lshlrev_b32_e32 v46, 16, v27
	v_and_b32_e32 v47, 0xffff0000, v27
	ds_write_b128 v2, v[44:47] offset:22400
	v_lshlrev_b32_e32 v48, 16, v28
	v_and_b32_e32 v49, 0xffff0000, v28
	v_lshlrev_b32_e32 v50, 16, v29
	v_and_b32_e32 v51, 0xffff0000, v29
	ds_write_b128 v2, v[48:51] offset:22656
	v_lshlrev_b32_e32 v52, 16, v32
	s_cmp_eq_u32 s41, 2
	s_cselect_b32 s2, 0, -1
	v_and_b32_e32 v52, s2, v52
	ds_write_b32 v8, v52 offset:21632
	s_mov_b32 s2, 0x00010001
	s_mov_b32 s3, 0x00010001
	s_mov_b64 exec, s[2:3]
	ds_write_b64 v9, v[34:35] offset:21632
	s_mov_b64 exec, -1
	s_add_u32 s24, s24, 0x1000
	s_addc_u32 s25, s25, 0
	s_add_u32 s26, s26, 0x2800
	s_addc_u32 s27, s27, 0
	s_add_u32 s28, s28, 0x100
	s_addc_u32 s29, s29, 0
	s_add_u32 s30, s30, s40
	s_addc_u32 s31, s31, 0
	s_waitcnt lgkmcnt(0)
	s_barrier
	s_cmp_eq_u32 s38, 63
	s_cbranch_scc1 .Lsc_o_nold
	global_load_dwordx4 v[20:23], v12, s[24:25]
	global_load_dwordx2 v[24:25], v13, s[26:27]
	global_load_dwordx2 v[26:27], v13, s[26:27] offset:128
	global_load_dwordx2 v[28:29], v13, s[26:27] offset:256
	global_load_dwordx2 v[30:31], v13, s[26:27] offset:384
	global_load_ushort v32, v14, s[26:27]
	global_load_dwordx2 v[34:35], v15, s[28:29]
; __device__ __forceinline__ void rwkv_scan2_item(const Params& p, int item, char* ldsraw) {
;     ...
;         for (int q = 0; q < 16; q++) {
;           const f32x4 cw = nw, ckk = nkk, ckka = nkka, ck = nk; const float cvA = nvA, cvB = nvB;
;           if (q < 15) R_LOAD(q + 1)
;           __builtin_amdgcn_sched_barrier(0);
;           float mA0 = mul_s(a0, ckk.x), mA1 = mul_s(a2, ckk.z), mB0 = mul_s(b0, ckk.x), mB1 = mul_s(b2, ckk.z);
;           mA0 = fma_s(a1, ckk.y, mA0); mA1 = fma_s(a3, ckk.w, mA1); mB0 = fma_s(b1, ckk.y, mB0); mB1 = fma_s(b3, ckk.w, mB1);
;           float psA = add_s(mA0, mA1), psB = add_s(mB0, mB1);
;           psA = row16_sum(psA); psB = row16_sum(psB);
;           { const float t0 = fnma_s(psA, ckka.x, mul_s(cvA, ck.x)), t1 = fnma_s(psA, ckka.y, mul_s(cvA, ck.y));
;             const float t2 = fnma_s(psA, ckka.z, mul_s(cvA, ck.z)), t3 = fnma_s(psA, ckka.w, mul_s(cvA, ck.w));
;             a0 = fma_s(a0, cw.x, t0); a1 = fma_s(a1, cw.y, t1); a2 = fma_s(a2, cw.z, t2); a3 = fma_s(a3, cw.w, t3); }
;           { const float t0 = fnma_s(psB, ckka.x, mul_s(cvB, ck.x)), t1 = fnma_s(psB, ckka.y, mul_s(cvB, ck.y));
;             const float t2 = fnma_s(psB, ckka.z, mul_s(cvB, ck.z)), t3 = fnma_s(psB, ckka.w, mul_s(cvB, ck.w));
;             b0 = fma_s(b0, cw.x, t0); b1 = fma_s(b1, cw.y, t1); b2 = fma_s(b2, cw.z, t2); b3 = fma_s(b3, cw.w, t3); }
;           sakA = sel_eq(sakA, psA, jl, q); sakB = sel_eq(sakB, psB, jl, q);
;         }
;     ...
;         SA[(c & 1) * 256 + jl * 16 + row8] = sakA; SA[(c & 1) * 256 + jl * 16 + 8 + row8] = sakB;
;       }
;     } else {
;       if (c >= 1) {
;         const float* d = buf + bprev * CH + jl * 4;
;         const float* dvp = buf + bprev * CH + 320 + row8;
;         const float* dcp = buf + bprev * CH + 336;
;         const float* sap = SA + ((c - 1) & 1) * 256 + row8;
;         f32x4 nw, nkka, nk, nwr; float nvA, nvB, nsA, nsB; f32x2 ncc;
;     ...
;         Y_LOAD(0)
;         float ykA = 0.f, ykB = 0.f;
; #pragma unroll
;         for (int q = 0; q < 16; q++) {
;           const f32x4 cw = nw, ckka = nkka, ck = nk, cwr = nwr; const float cvA = nvA, cvB = nvB, psA = nsA, psB = nsB; const f32x2 ccc = ncc;
;           if (q < 15) Y_LOAD(q + 1)
;           __builtin_amdgcn_sched_barrier(0);
;           float nA0 = mul_s(a0, cwr.x), nA1 = mul_s(a2, cwr.z), nB0 = mul_s(b0, cwr.x), nB1 = mul_s(b2, cwr.z);
.Lsc_o_nold:
	ds_read_b128 v[44:47], v0 offset:21888
	ds_read_b128 v[48:51], v0 offset:22144
	ds_read_b128 v[56:59], v0 offset:22656
	ds_read_b128 v[40:43], v0 offset:21632
	ds_read_b128 v[52:55], v0 offset:22400
	ds_read_b128 v[80:83], v1 offset:21632
	ds_read_b128 v[64:67], v0 offset:23168
	ds_read_b128 v[68:71], v0 offset:23424
	ds_read_b128 v[76:79], v0 offset:23936
	ds_read_b128 v[60:63], v0 offset:22912
	ds_read_b128 v[72:75], v0 offset:23680
	s_waitcnt lgkmcnt(9)
	v_pk_mul_f32 v[88:89], v[4:5], v[44:45] op_sel_hi:[0,1]
	v_pk_mul_f32 v[90:91], v[6:7], v[48:49] op_sel_hi:[0,1]
	v_pk_fma_f32 v[88:89], v[4:5], v[46:47], v[88:89] op_sel:[1,0,0] op_sel_hi:[1,1,1]
	v_pk_fma_f32 v[90:91], v[6:7], v[50:51], v[90:91] op_sel:[1,0,0] op_sel_hi:[1,1,1]
	v_pk_add_f32 v[100:101], v[88:89], v[90:91]
	s_waitcnt lgkmcnt(5)
	v_pk_mul_f32 v[96:97], v[80:81], v[56:57] op_sel:[0,0] op_sel_hi:[0,1]
	v_pk_mul_f32 v[98:99], v[80:81], v[58:59] op_sel:[0,0] op_sel_hi:[0,1]
	v_add_f32_dpp v93, v100, v100 quad_perm:[1,0,3,2] row_mask:0xf bank_mask:0xf
	v_pk_fma_f32 v[96:97], v[4:5], v[40:41], v[96:97]
	v_pk_fma_f32 v[98:99], v[6:7], v[42:43], v[98:99]
	v_add_f32_dpp v92, v93, v93 quad_perm:[2,3,0,1] row_mask:0xf bank_mask:0xf
	ds_read_b128 v[142:145], v0 offset:24448
	ds_read_b128 v[146:149], v0 offset:24704
	v_add_f32_dpp v93, v92, v92 row_ror:4 row_mask:0xf bank_mask:0xf
	ds_read_b128 v[154:157], v0 offset:25216
	ds_read_b128 v[138:141], v0 offset:24192
	v_add_f32_dpp v94, v93, v93 row_ror:8 row_mask:0xf bank_mask:0xf
	v_add_f32_dpp v108, v93, v93 row_ror:8 row_mask:0xf bank_mask:0x1
	ds_read_b128 v[150:153], v0 offset:24960
	v_pk_fma_f32 v[4:5], v[94:95], v[52:53], v[96:97] op_sel_hi:[0,1,1] neg_lo:[1,0,0] neg_hi:[1,0,0]
	v_pk_fma_f32 v[6:7], v[94:95], v[54:55], v[98:99] op_sel_hi:[0,1,1] neg_lo:[1,0,0] neg_hi:[1,0,0]
	s_waitcnt lgkmcnt(8)
	v_pk_mul_f32 v[88:89], v[4:5], v[64:65] op_sel_hi:[0,1]
	v_pk_mul_f32 v[90:91], v[6:7], v[68:69] op_sel_hi:[0,1]
	v_pk_fma_f32 v[88:89], v[4:5], v[66:67], v[88:89] op_sel:[1,0,0] op_sel_hi:[1,1,1]
	v_pk_fma_f32 v[90:91], v[6:7], v[70:71], v[90:91] op_sel:[1,0,0] op_sel_hi:[1,1,1]
	v_pk_add_f32 v[102:103], v[88:89], v[90:91]
	s_waitcnt lgkmcnt(7)
	v_pk_mul_f32 v[96:97], v[80:81], v[76:77] op_sel:[1,0] op_sel_hi:[1,1]
	v_pk_mul_f32 v[98:99], v[80:81], v[78:79] op_sel:[1,0] op_sel_hi:[1,1]
	v_add_f32_dpp v93, v102, v102 quad_perm:[1,0,3,2] row_mask:0xf bank_mask:0xf
	s_waitcnt lgkmcnt(6)
	v_pk_fma_f32 v[96:97], v[4:5], v[60:61], v[96:97]
	v_pk_fma_f32 v[98:99], v[6:7], v[62:63], v[98:99]
	v_add_f32_dpp v92, v93, v93 quad_perm:[2,3,0,1] row_mask:0xf bank_mask:0xf
	ds_read_b128 v[44:47], v0 offset:25728
	ds_read_b128 v[48:51], v0 offset:25984
	v_add_f32_dpp v93, v92, v92 row_ror:4 row_mask:0xf bank_mask:0xf
	ds_read_b128 v[56:59], v0 offset:26496
	ds_read_b128 v[40:43], v0 offset:25472
	v_add_f32_dpp v94, v93, v93 row_ror:8 row_mask:0xf bank_mask:0xf
	v_add_f32_dpp v108, v93, v93 row_ror:8 row_mask:0xf bank_mask:0x4
	ds_read_b128 v[52:55], v0 offset:26240
	s_waitcnt lgkmcnt(10)
	v_pk_fma_f32 v[4:5], v[94:95], v[72:73], v[96:97] op_sel_hi:[0,1,1] neg_lo:[1,0,0] neg_hi:[1,0,0]
	v_pk_fma_f32 v[6:7], v[94:95], v[74:75], v[98:99] op_sel_hi:[0,1,1] neg_lo:[1,0,0] neg_hi:[1,0,0]
	ds_read_b128 v[84:87], v1 offset:21648
	v_add_f32_dpp v101, v101, v101 row_ror:8 row_mask:0xf bank_mask:0x3
	s_nop 1
	v_add_f32_dpp v101, v103, v103 row_ror:8 row_mask:0xf bank_mask:0xc
	s_waitcnt lgkmcnt(9)
	v_pk_mul_f32 v[88:89], v[4:5], v[142:143] op_sel_hi:[0,1]
	v_pk_mul_f32 v[90:91], v[6:7], v[146:147] op_sel_hi:[0,1]
	v_pk_fma_f32 v[88:89], v[4:5], v[144:145], v[88:89] op_sel:[1,0,0] op_sel_hi:[1,1,1]
	v_pk_fma_f32 v[90:91], v[6:7], v[148:149], v[90:91] op_sel:[1,0,0] op_sel_hi:[1,1,1]
	v_pk_add_f32 v[104:105], v[88:89], v[90:91]
	s_waitcnt lgkmcnt(8)
	v_pk_mul_f32 v[96:97], v[82:83], v[154:155] op_sel:[0,0] op_sel_hi:[0,1]
	v_pk_mul_f32 v[98:99], v[82:83], v[156:157] op_sel:[0,0] op_sel_hi:[0,1]
	v_add_f32_dpp v93, v104, v104 quad_perm:[1,0,3,2] row_mask:0xf bank_mask:0xf
	s_waitcnt lgkmcnt(7)
	v_pk_fma_f32 v[96:97], v[4:5], v[138:139], v[96:97]
	v_pk_fma_f32 v[98:99], v[6:7], v[140:141], v[98:99]
	v_add_f32_dpp v92, v93, v93 quad_perm:[2,3,0,1] row_mask:0xf bank_mask:0xf
	ds_read_b128 v[64:67], v0 offset:27008
	ds_read_b128 v[68:71], v0 offset:27264
	v_add_f32_dpp v93, v92, v92 row_ror:4 row_mask:0xf bank_mask:0xf
	ds_read_b128 v[76:79], v0 offset:27776
	ds_read_b128 v[60:63], v0 offset:26752
	v_add_f32_dpp v94, v93, v93 row_ror:8 row_mask:0xf bank_mask:0xf
	v_add_f32_dpp v108, v93, v93 row_ror:8 row_mask:0xf bank_mask:0x2
	ds_read_b128 v[72:75], v0 offset:27520
	s_waitcnt lgkmcnt(11)
	v_pk_fma_f32 v[4:5], v[94:95], v[150:151], v[96:97] op_sel_hi:[0,1,1] neg_lo:[1,0,0] neg_hi:[1,0,0]
	v_pk_fma_f32 v[6:7], v[94:95], v[152:153], v[98:99] op_sel_hi:[0,1,1] neg_lo:[1,0,0] neg_hi:[1,0,0]
	s_waitcnt lgkmcnt(9)
	v_pk_mul_f32 v[88:89], v[4:5], v[44:45] op_sel_hi:[0,1]
	v_pk_mul_f32 v[90:91], v[6:7], v[48:49] op_sel_hi:[0,1]
	v_pk_fma_f32 v[88:89], v[4:5], v[46:47], v[88:89] op_sel:[1,0,0] op_sel_hi:[1,1,1]
	v_pk_fma_f32 v[90:91], v[6:7], v[50:51], v[90:91] op_sel:[1,0,0] op_sel_hi:[1,1,1]
	v_pk_add_f32 v[132:133], v[88:89], v[90:91]
	s_waitcnt lgkmcnt(8)
	v_pk_mul_f32 v[96:97], v[82:83], v[56:57] op_sel:[1,0] op_sel_hi:[1,1]
	v_pk_mul_f32 v[98:99], v[82:83], v[58:59] op_sel:[1,0] op_sel_hi:[1,1]
	v_add_f32_dpp v93, v132, v132 quad_perm:[1,0,3,2] row_mask:0xf bank_mask:0xf
	s_waitcnt lgkmcnt(7)
; __device__ __forceinline__ float fma_s(float a, float b, float c) { float d; asm("v_fma_f32 %0, %1, %2, %3" : "=v"(d) : "v"(a), "v"(b), "v"(c)); return d; }
; __device__ __forceinline__ float fnma_s(float a, float b, float c) { float d; asm("v_fma_f32 %0, -%1, %2, %3" : "=v"(d) : "v"(a), "v"(b), "v"(c)); return d; }
; __device__ __forceinline__ float mul_s(float a, float b) { float d; asm("v_mul_f32 %0, %1, %2" : "=v"(d) : "v"(a), "v"(b)); return d; }
; __device__ __forceinline__ float add_s(float a, float b) { float d; asm("v_add_f32 %0, %1, %2" : "=v"(d) : "v"(a), "v"(b)); return d; }
; __device__ __forceinline__ float sel_eq(float keep, float v, int a, int b) { asm("v_cmp_eq_u32 vcc, %1, %2\n\tv_cndmask_b32 %0, %0, %3, vcc" : "+v"(keep) : "v"(a), "v"(b), "v"(v) : "vcc"); return keep; }
; template <int VAR>
; __device__ __forceinline__ void rwkv_scan_item(const Params& p, int item, char* ldsraw) {
;     ...
;     for (int q = 0; q < (VAR == 4 ? 0 : 16); q++) {
;       const f32x4 cw = nw, ckk = nkk, ckka = nkka, ck = nk, cwr = nwr; const float cv = nv; const f32x2 ccc = ncc;
;       if (q < 15 && VAR != 3) SCAN_LOAD(q + 1)
;       __builtin_amdgcn_sched_barrier(0);
;       float m0 = mul_s(s0, ckk.x), m1 = mul_s(s2, ckk.z), n0 = mul_s(s0, cwr.x), n1 = mul_s(s2, cwr.z);
;       m0 = fma_s(s1, ckk.y, m0); m1 = fma_s(s3, ckk.w, m1); n0 = fma_s(s1, cwr.y, n0); n1 = fma_s(s3, cwr.w, n1);
;       float psa = add_s(m0, m1), pu = add_s(n0, n1);
;       if (VAR != 2) { psa = row16_sum(psa); pu = row16_sum(pu); }
;       const float t0 = fnma_s(psa, ckka.x, mul_s(cv, ck.x)), t1 = fnma_s(psa, ckka.y, mul_s(cv, ck.y));
;       const float t2 = fnma_s(psa, ckka.z, mul_s(cv, ck.z)), t3 = fnma_s(psa, ckka.w, mul_s(cv, ck.w));
;       s0 = fma_s(s0, cw.x, t0); s1 = fma_s(s1, cw.y, t1); s2 = fma_s(s2, cw.z, t2); s3 = fma_s(s3, cw.w, t3);
;       const float y = fnma_s(psa, ccc.x, fma_s(cv, ccc.y, pu));
;       ykeep = sel_eq(ykeep, y, jl, q);
;     }
	v_pk_fma_f32 v[96:97], v[4:5], v[40:41], v[96:97]
	v_pk_fma_f32 v[98:99], v[6:7], v[42:43], v[98:99]
	v_add_f32_dpp v92, v93, v93 quad_perm:[2,3,0,1] row_mask:0xf bank_mask:0xf
	ds_read_b128 v[142:145], v0 offset:28288
	ds_read_b128 v[146:149], v0 offset:28544
	v_add_f32_dpp v93, v92, v92 row_ror:4 row_mask:0xf bank_mask:0xf
	ds_read_b128 v[154:157], v0 offset:29056
	ds_read_b128 v[138:141], v0 offset:28032
	v_add_f32_dpp v94, v93, v93 row_ror:8 row_mask:0xf bank_mask:0xf
	v_add_f32_dpp v108, v93, v93 row_ror:8 row_mask:0xf bank_mask:0x8
	ds_read_b128 v[150:153], v0 offset:28800
	s_waitcnt lgkmcnt(11)
	v_pk_fma_f32 v[4:5], v[94:95], v[52:53], v[96:97] op_sel_hi:[0,1,1] neg_lo:[1,0,0] neg_hi:[1,0,0]
	v_pk_fma_f32 v[6:7], v[94:95], v[54:55], v[98:99] op_sel_hi:[0,1,1] neg_lo:[1,0,0] neg_hi:[1,0,0]
	v_add_f32_dpp v105, v105, v105 row_ror:8 row_mask:0xf bank_mask:0x3
	s_nop 1
	v_add_f32_dpp v105, v133, v133 row_ror:8 row_mask:0xf bank_mask:0xc
	v_add_f32_dpp v101, v101, v101 row_half_mirror row_mask:0xf bank_mask:0x5
	s_nop 1
	v_add_f32_dpp v101, v105, v105 row_half_mirror row_mask:0xf bank_mask:0xa
	s_waitcnt lgkmcnt(8)
	v_pk_mul_f32 v[88:89], v[4:5], v[64:65] op_sel_hi:[0,1]
	v_pk_mul_f32 v[90:91], v[6:7], v[68:69] op_sel_hi:[0,1]
	v_pk_fma_f32 v[88:89], v[4:5], v[66:67], v[88:89] op_sel:[1,0,0] op_sel_hi:[1,1,1]
	v_pk_fma_f32 v[90:91], v[6:7], v[70:71], v[90:91] op_sel:[1,0,0] op_sel_hi:[1,1,1]
	v_pk_add_f32 v[134:135], v[88:89], v[90:91]
	s_waitcnt lgkmcnt(7)
	v_pk_mul_f32 v[96:97], v[84:85], v[76:77] op_sel:[0,0] op_sel_hi:[0,1]
	v_pk_mul_f32 v[98:99], v[84:85], v[78:79] op_sel:[0,0] op_sel_hi:[0,1]
	v_add_f32_dpp v93, v134, v134 quad_perm:[1,0,3,2] row_mask:0xf bank_mask:0xf
	s_waitcnt lgkmcnt(6)
	v_pk_fma_f32 v[96:97], v[4:5], v[60:61], v[96:97]
	v_pk_fma_f32 v[98:99], v[6:7], v[62:63], v[98:99]
	v_add_f32_dpp v92, v93, v93 quad_perm:[2,3,0,1] row_mask:0xf bank_mask:0xf
	ds_read_b128 v[44:47], v0 offset:29568
	ds_read_b128 v[48:51], v0 offset:29824
	v_add_f32_dpp v93, v92, v92 row_ror:4 row_mask:0xf bank_mask:0xf
	ds_read_b128 v[56:59], v0 offset:30336
	ds_read_b128 v[40:43], v0 offset:29312
	v_add_f32_dpp v94, v93, v93 row_ror:8 row_mask:0xf bank_mask:0xf
	v_add_f32_dpp v109, v93, v93 row_ror:8 row_mask:0xf bank_mask:0x1
	ds_read_b128 v[52:55], v0 offset:30080
	s_waitcnt lgkmcnt(10)
	v_pk_fma_f32 v[4:5], v[94:95], v[72:73], v[96:97] op_sel_hi:[0,1,1] neg_lo:[1,0,0] neg_hi:[1,0,0]
	v_pk_fma_f32 v[6:7], v[94:95], v[74:75], v[98:99] op_sel_hi:[0,1,1] neg_lo:[1,0,0] neg_hi:[1,0,0]
	s_waitcnt lgkmcnt(8)
	v_pk_mul_f32 v[88:89], v[4:5], v[142:143] op_sel_hi:[0,1]
	v_pk_mul_f32 v[90:91], v[6:7], v[146:147] op_sel_hi:[0,1]
	v_pk_fma_f32 v[88:89], v[4:5], v[144:145], v[88:89] op_sel:[1,0,0] op_sel_hi:[1,1,1]
	v_pk_fma_f32 v[90:91], v[6:7], v[148:149], v[90:91] op_sel:[1,0,0] op_sel_hi:[1,1,1]
	v_pk_add_f32 v[136:137], v[88:89], v[90:91]
	s_waitcnt lgkmcnt(7)
	v_pk_mul_f32 v[96:97], v[84:85], v[154:155] op_sel:[1,0] op_sel_hi:[1,1]
	v_pk_mul_f32 v[98:99], v[84:85], v[156:157] op_sel:[1,0] op_sel_hi:[1,1]
	v_add_f32_dpp v93, v136, v136 quad_perm:[1,0,3,2] row_mask:0xf bank_mask:0xf
	s_waitcnt lgkmcnt(6)
	v_pk_fma_f32 v[96:97], v[4:5], v[138:139], v[96:97]
	v_pk_fma_f32 v[98:99], v[6:7], v[140:141], v[98:99]
	v_add_f32_dpp v92, v93, v93 quad_perm:[2,3,0,1] row_mask:0xf bank_mask:0xf
	ds_read_b128 v[64:67], v0 offset:30848
	ds_read_b128 v[68:71], v0 offset:31104
	v_add_f32_dpp v93, v92, v92 row_ror:4 row_mask:0xf bank_mask:0xf
	ds_read_b128 v[76:79], v0 offset:31616
	ds_read_b128 v[60:63], v0 offset:30592
	v_add_f32_dpp v94, v93, v93 row_ror:8 row_mask:0xf bank_mask:0xf
	v_add_f32_dpp v109, v93, v93 row_ror:8 row_mask:0xf bank_mask:0x4
	ds_read_b128 v[72:75], v0 offset:31360
	s_waitcnt lgkmcnt(10)
	v_pk_fma_f32 v[4:5], v[94:95], v[150:151], v[96:97] op_sel_hi:[0,1,1] neg_lo:[1,0,0] neg_hi:[1,0,0]
	v_pk_fma_f32 v[6:7], v[94:95], v[152:153], v[98:99] op_sel_hi:[0,1,1] neg_lo:[1,0,0] neg_hi:[1,0,0]
	ds_read_b128 v[80:83], v1 offset:21664
	v_add_f32_dpp v135, v135, v135 row_ror:8 row_mask:0xf bank_mask:0x3
	s_nop 1
	v_add_f32_dpp v135, v137, v137 row_ror:8 row_mask:0xf bank_mask:0xc
	s_waitcnt lgkmcnt(9)
	v_pk_mul_f32 v[88:89], v[4:5], v[44:45] op_sel_hi:[0,1]
	v_pk_mul_f32 v[90:91], v[6:7], v[48:49] op_sel_hi:[0,1]
	v_pk_fma_f32 v[88:89], v[4:5], v[46:47], v[88:89] op_sel:[1,0,0] op_sel_hi:[1,1,1]
	v_pk_fma_f32 v[90:91], v[6:7], v[50:51], v[90:91] op_sel:[1,0,0] op_sel_hi:[1,1,1]
	v_pk_add_f32 v[102:103], v[88:89], v[90:91]
	s_waitcnt lgkmcnt(8)
	v_pk_mul_f32 v[96:97], v[86:87], v[56:57] op_sel:[0,0] op_sel_hi:[0,1]
	v_pk_mul_f32 v[98:99], v[86:87], v[58:59] op_sel:[0,0] op_sel_hi:[0,1]
	v_add_f32_dpp v93, v102, v102 quad_perm:[1,0,3,2] row_mask:0xf bank_mask:0xf
	s_waitcnt lgkmcnt(7)
	v_pk_fma_f32 v[96:97], v[4:5], v[40:41], v[96:97]
	v_pk_fma_f32 v[98:99], v[6:7], v[42:43], v[98:99]
	v_add_f32_dpp v92, v93, v93 quad_perm:[2,3,0,1] row_mask:0xf bank_mask:0xf
	ds_read_b128 v[142:145], v0 offset:32128
	ds_read_b128 v[146:149], v0 offset:32384
	v_add_f32_dpp v93, v92, v92 row_ror:4 row_mask:0xf bank_mask:0xf
	ds_read_b128 v[154:157], v0 offset:32896
	ds_read_b128 v[138:141], v0 offset:31872
	v_add_f32_dpp v94, v93, v93 row_ror:8 row_mask:0xf bank_mask:0xf
	v_add_f32_dpp v109, v93, v93 row_ror:8 row_mask:0xf bank_mask:0x2
	ds_read_b128 v[150:153], v0 offset:32640
	s_waitcnt lgkmcnt(11)
	v_pk_fma_f32 v[4:5], v[94:95], v[52:53], v[96:97] op_sel_hi:[0,1,1] neg_lo:[1,0,0] neg_hi:[1,0,0]
	v_pk_fma_f32 v[6:7], v[94:95], v[54:55], v[98:99] op_sel_hi:[0,1,1] neg_lo:[1,0,0] neg_hi:[1,0,0]
	s_waitcnt lgkmcnt(9)
; __device__ __forceinline__ float fma_s(float a, float b, float c) { float d; asm("v_fma_f32 %0, %1, %2, %3" : "=v"(d) : "v"(a), "v"(b), "v"(c)); return d; }
; __device__ __forceinline__ float fnma_s(float a, float b, float c) { float d; asm("v_fma_f32 %0, -%1, %2, %3" : "=v"(d) : "v"(a), "v"(b), "v"(c)); return d; }
; __device__ __forceinline__ float mul_s(float a, float b) { float d; asm("v_mul_f32 %0, %1, %2" : "=v"(d) : "v"(a), "v"(b)); return d; }
; __device__ __forceinline__ float add_s(float a, float b) { float d; asm("v_add_f32 %0, %1, %2" : "=v"(d) : "v"(a), "v"(b)); return d; }
; __device__ __forceinline__ float sel_eq(float keep, float v, int a, int b) { asm("v_cmp_eq_u32 vcc, %1, %2\n\tv_cndmask_b32 %0, %0, %3, vcc" : "+v"(keep) : "v"(a), "v"(b), "v"(v) : "vcc"); return keep; }
; template <int VAR>
; __device__ __forceinline__ void rwkv_scan_item(const Params& p, int item, char* ldsraw) {
;     ...
;     for (int q = 0; q < (VAR == 4 ? 0 : 16); q++) {
;       const f32x4 cw = nw, ckk = nkk, ckka = nkka, ck = nk, cwr = nwr; const float cv = nv; const f32x2 ccc = ncc;
;       if (q < 15 && VAR != 3) SCAN_LOAD(q + 1)
;       __builtin_amdgcn_sched_barrier(0);
;       float m0 = mul_s(s0, ckk.x), m1 = mul_s(s2, ckk.z), n0 = mul_s(s0, cwr.x), n1 = mul_s(s2, cwr.z);
;       m0 = fma_s(s1, ckk.y, m0); m1 = fma_s(s3, ckk.w, m1); n0 = fma_s(s1, cwr.y, n0); n1 = fma_s(s3, cwr.w, n1);
;       float psa = add_s(m0, m1), pu = add_s(n0, n1);
;       if (VAR != 2) { psa = row16_sum(psa); pu = row16_sum(pu); }
;       const float t0 = fnma_s(psa, ckka.x, mul_s(cv, ck.x)), t1 = fnma_s(psa, ckka.y, mul_s(cv, ck.y));
;       const float t2 = fnma_s(psa, ckka.z, mul_s(cv, ck.z)), t3 = fnma_s(psa, ckka.w, mul_s(cv, ck.w));
;       s0 = fma_s(s0, cw.x, t0); s1 = fma_s(s1, cw.y, t1); s2 = fma_s(s2, cw.z, t2); s3 = fma_s(s3, cw.w, t3);
;       const float y = fnma_s(psa, ccc.x, fma_s(cv, ccc.y, pu));
;       ykeep = sel_eq(ykeep, y, jl, q);
;     }
	v_pk_mul_f32 v[88:89], v[4:5], v[64:65] op_sel_hi:[0,1]
	v_pk_mul_f32 v[90:91], v[6:7], v[68:69] op_sel_hi:[0,1]
	v_pk_fma_f32 v[88:89], v[4:5], v[66:67], v[88:89] op_sel:[1,0,0] op_sel_hi:[1,1,1]
	v_pk_fma_f32 v[90:91], v[6:7], v[70:71], v[90:91] op_sel:[1,0,0] op_sel_hi:[1,1,1]
	v_pk_add_f32 v[132:133], v[88:89], v[90:91]
	s_waitcnt lgkmcnt(8)
	v_pk_mul_f32 v[96:97], v[86:87], v[76:77] op_sel:[1,0] op_sel_hi:[1,1]
	v_pk_mul_f32 v[98:99], v[86:87], v[78:79] op_sel:[1,0] op_sel_hi:[1,1]
	v_add_f32_dpp v93, v132, v132 quad_perm:[1,0,3,2] row_mask:0xf bank_mask:0xf
	s_waitcnt lgkmcnt(7)
	v_pk_fma_f32 v[96:97], v[4:5], v[60:61], v[96:97]
	v_pk_fma_f32 v[98:99], v[6:7], v[62:63], v[98:99]
	v_add_f32_dpp v92, v93, v93 quad_perm:[2,3,0,1] row_mask:0xf bank_mask:0xf
	ds_read_b128 v[44:47], v0 offset:33408
	ds_read_b128 v[48:51], v0 offset:33664
	v_add_f32_dpp v93, v92, v92 row_ror:4 row_mask:0xf bank_mask:0xf
	ds_read_b128 v[56:59], v0 offset:34176
	ds_read_b128 v[40:43], v0 offset:33152
	v_add_f32_dpp v94, v93, v93 row_ror:8 row_mask:0xf bank_mask:0xf
	v_add_f32_dpp v109, v93, v93 row_ror:8 row_mask:0xf bank_mask:0x8
	ds_read_b128 v[52:55], v0 offset:33920
	s_waitcnt lgkmcnt(11)
	v_pk_fma_f32 v[4:5], v[94:95], v[72:73], v[96:97] op_sel_hi:[0,1,1] neg_lo:[1,0,0] neg_hi:[1,0,0]
	v_pk_fma_f32 v[6:7], v[94:95], v[74:75], v[98:99] op_sel_hi:[0,1,1] neg_lo:[1,0,0] neg_hi:[1,0,0]
	v_add_f32_dpp v103, v103, v103 row_ror:8 row_mask:0xf bank_mask:0x3
	s_nop 1
	v_add_f32_dpp v103, v133, v133 row_ror:8 row_mask:0xf bank_mask:0xc
	v_add_f32_dpp v135, v135, v135 row_half_mirror row_mask:0xf bank_mask:0x5
	s_nop 1
	v_add_f32_dpp v135, v103, v103 row_half_mirror row_mask:0xf bank_mask:0xa
	v_cndmask_b32_e64 v106, v135, v101, s[36:37]
	v_cndmask_b32_e64 v107, v101, v135, s[36:37]
	s_nop 1
	v_add_f32_dpp v101, v106, v107 quad_perm:[2,3,0,1] row_mask:0xf bank_mask:0xf
	s_waitcnt lgkmcnt(8)
	v_pk_mul_f32 v[88:89], v[4:5], v[142:143] op_sel_hi:[0,1]
	v_pk_mul_f32 v[90:91], v[6:7], v[146:147] op_sel_hi:[0,1]
	v_pk_fma_f32 v[88:89], v[4:5], v[144:145], v[88:89] op_sel:[1,0,0] op_sel_hi:[1,1,1]
	v_pk_fma_f32 v[90:91], v[6:7], v[148:149], v[90:91] op_sel:[1,0,0] op_sel_hi:[1,1,1]
	v_pk_add_f32 v[104:105], v[88:89], v[90:91]
	s_waitcnt lgkmcnt(7)
	v_pk_mul_f32 v[96:97], v[80:81], v[154:155] op_sel:[0,0] op_sel_hi:[0,1]
	v_pk_mul_f32 v[98:99], v[80:81], v[156:157] op_sel:[0,0] op_sel_hi:[0,1]
	v_add_f32_dpp v93, v104, v104 quad_perm:[1,0,3,2] row_mask:0xf bank_mask:0xf
	s_waitcnt lgkmcnt(6)
	v_pk_fma_f32 v[96:97], v[4:5], v[138:139], v[96:97]
	v_pk_fma_f32 v[98:99], v[6:7], v[140:141], v[98:99]
	v_add_f32_dpp v92, v93, v93 quad_perm:[2,3,0,1] row_mask:0xf bank_mask:0xf
	ds_read_b128 v[64:67], v0 offset:34688
	ds_read_b128 v[68:71], v0 offset:34944
	v_add_f32_dpp v93, v92, v92 row_ror:4 row_mask:0xf bank_mask:0xf
	ds_read_b128 v[76:79], v0 offset:35456
	ds_read_b128 v[60:63], v0 offset:34432
	v_add_f32_dpp v94, v93, v93 row_ror:8 row_mask:0xf bank_mask:0xf
	v_add_f32_dpp v110, v93, v93 row_ror:8 row_mask:0xf bank_mask:0x1
	ds_read_b128 v[72:75], v0 offset:35200
	s_waitcnt lgkmcnt(10)
	v_pk_fma_f32 v[4:5], v[94:95], v[150:151], v[96:97] op_sel_hi:[0,1,1] neg_lo:[1,0,0] neg_hi:[1,0,0]
	v_pk_fma_f32 v[6:7], v[94:95], v[152:153], v[98:99] op_sel_hi:[0,1,1] neg_lo:[1,0,0] neg_hi:[1,0,0]
	s_waitcnt lgkmcnt(8)
	v_pk_mul_f32 v[88:89], v[4:5], v[44:45] op_sel_hi:[0,1]
	v_pk_mul_f32 v[90:91], v[6:7], v[48:49] op_sel_hi:[0,1]
	v_pk_fma_f32 v[88:89], v[4:5], v[46:47], v[88:89] op_sel:[1,0,0] op_sel_hi:[1,1,1]
	v_pk_fma_f32 v[90:91], v[6:7], v[50:51], v[90:91] op_sel:[1,0,0] op_sel_hi:[1,1,1]
	v_pk_add_f32 v[136:137], v[88:89], v[90:91]
	s_waitcnt lgkmcnt(7)
	v_pk_mul_f32 v[96:97], v[80:81], v[56:57] op_sel:[1,0] op_sel_hi:[1,1]
	v_pk_mul_f32 v[98:99], v[80:81], v[58:59] op_sel:[1,0] op_sel_hi:[1,1]
	v_add_f32_dpp v93, v136, v136 quad_perm:[1,0,3,2] row_mask:0xf bank_mask:0xf
	s_waitcnt lgkmcnt(6)
	v_pk_fma_f32 v[96:97], v[4:5], v[40:41], v[96:97]
	v_pk_fma_f32 v[98:99], v[6:7], v[42:43], v[98:99]
	v_add_f32_dpp v92, v93, v93 quad_perm:[2,3,0,1] row_mask:0xf bank_mask:0xf
	ds_read_b128 v[142:145], v0 offset:35968
	ds_read_b128 v[146:149], v0 offset:36224
	v_add_f32_dpp v93, v92, v92 row_ror:4 row_mask:0xf bank_mask:0xf
	ds_read_b128 v[154:157], v0 offset:36736
	ds_read_b128 v[138:141], v0 offset:35712
	v_add_f32_dpp v94, v93, v93 row_ror:8 row_mask:0xf bank_mask:0xf
	v_add_f32_dpp v110, v93, v93 row_ror:8 row_mask:0xf bank_mask:0x4
	ds_read_b128 v[150:153], v0 offset:36480
	s_waitcnt lgkmcnt(10)
	v_pk_fma_f32 v[4:5], v[94:95], v[52:53], v[96:97] op_sel_hi:[0,1,1] neg_lo:[1,0,0] neg_hi:[1,0,0]
	v_pk_fma_f32 v[6:7], v[94:95], v[54:55], v[98:99] op_sel_hi:[0,1,1] neg_lo:[1,0,0] neg_hi:[1,0,0]
	ds_read_b128 v[84:87], v1 offset:21680
	v_add_f32_dpp v105, v105, v105 row_ror:8 row_mask:0xf bank_mask:0x3
	s_nop 1
	v_add_f32_dpp v105, v137, v137 row_ror:8 row_mask:0xf bank_mask:0xc
	s_waitcnt lgkmcnt(9)
	v_pk_mul_f32 v[88:89], v[4:5], v[64:65] op_sel_hi:[0,1]
	v_pk_mul_f32 v[90:91], v[6:7], v[68:69] op_sel_hi:[0,1]
	v_pk_fma_f32 v[88:89], v[4:5], v[66:67], v[88:89] op_sel:[1,0,0] op_sel_hi:[1,1,1]
	v_pk_fma_f32 v[90:91], v[6:7], v[70:71], v[90:91] op_sel:[1,0,0] op_sel_hi:[1,1,1]
	v_pk_add_f32 v[132:133], v[88:89], v[90:91]
	s_waitcnt lgkmcnt(8)
	v_pk_mul_f32 v[96:97], v[82:83], v[76:77] op_sel:[0,0] op_sel_hi:[0,1]
	v_pk_mul_f32 v[98:99], v[82:83], v[78:79] op_sel:[0,0] op_sel_hi:[0,1]
	v_add_f32_dpp v93, v132, v132 quad_perm:[1,0,3,2] row_mask:0xf bank_mask:0xf
	s_waitcnt lgkmcnt(7)
; __device__ __forceinline__ float fma_s(float a, float b, float c) { float d; asm("v_fma_f32 %0, %1, %2, %3" : "=v"(d) : "v"(a), "v"(b), "v"(c)); return d; }
; __device__ __forceinline__ float fnma_s(float a, float b, float c) { float d; asm("v_fma_f32 %0, -%1, %2, %3" : "=v"(d) : "v"(a), "v"(b), "v"(c)); return d; }
; __device__ __forceinline__ float mul_s(float a, float b) { float d; asm("v_mul_f32 %0, %1, %2" : "=v"(d) : "v"(a), "v"(b)); return d; }
; __device__ __forceinline__ float add_s(float a, float b) { float d; asm("v_add_f32 %0, %1, %2" : "=v"(d) : "v"(a), "v"(b)); return d; }
; __device__ __forceinline__ float sel_eq(float keep, float v, int a, int b) { asm("v_cmp_eq_u32 vcc, %1, %2\n\tv_cndmask_b32 %0, %0, %3, vcc" : "+v"(keep) : "v"(a), "v"(b), "v"(v) : "vcc"); return keep; }
; template <int VAR>
; __device__ __forceinline__ void rwkv_scan_item(const Params& p, int item, char* ldsraw) {
;     ...
;     for (int q = 0; q < (VAR == 4 ? 0 : 16); q++) {
;       const f32x4 cw = nw, ckk = nkk, ckka = nkka, ck = nk, cwr = nwr; const float cv = nv; const f32x2 ccc = ncc;
;       if (q < 15 && VAR != 3) SCAN_LOAD(q + 1)
;       __builtin_amdgcn_sched_barrier(0);
;       float m0 = mul_s(s0, ckk.x), m1 = mul_s(s2, ckk.z), n0 = mul_s(s0, cwr.x), n1 = mul_s(s2, cwr.z);
;       m0 = fma_s(s1, ckk.y, m0); m1 = fma_s(s3, ckk.w, m1); n0 = fma_s(s1, cwr.y, n0); n1 = fma_s(s3, cwr.w, n1);
;       float psa = add_s(m0, m1), pu = add_s(n0, n1);
;       if (VAR != 2) { psa = row16_sum(psa); pu = row16_sum(pu); }
;       const float t0 = fnma_s(psa, ckka.x, mul_s(cv, ck.x)), t1 = fnma_s(psa, ckka.y, mul_s(cv, ck.y));
;       const float t2 = fnma_s(psa, ckka.z, mul_s(cv, ck.z)), t3 = fnma_s(psa, ckka.w, mul_s(cv, ck.w));
;       s0 = fma_s(s0, cw.x, t0); s1 = fma_s(s1, cw.y, t1); s2 = fma_s(s2, cw.z, t2); s3 = fma_s(s3, cw.w, t3);
;       const float y = fnma_s(psa, ccc.x, fma_s(cv, ccc.y, pu));
;       ykeep = sel_eq(ykeep, y, jl, q);
;     }
	v_pk_fma_f32 v[96:97], v[4:5], v[60:61], v[96:97]
	v_pk_fma_f32 v[98:99], v[6:7], v[62:63], v[98:99]
	v_add_f32_dpp v92, v93, v93 quad_perm:[2,3,0,1] row_mask:0xf bank_mask:0xf
	ds_read_b128 v[44:47], v0 offset:37248
	ds_read_b128 v[48:51], v0 offset:37504
	v_add_f32_dpp v93, v92, v92 row_ror:4 row_mask:0xf bank_mask:0xf
	ds_read_b128 v[56:59], v0 offset:38016
	ds_read_b128 v[40:43], v0 offset:36992
	v_add_f32_dpp v94, v93, v93 row_ror:8 row_mask:0xf bank_mask:0xf
	v_add_f32_dpp v110, v93, v93 row_ror:8 row_mask:0xf bank_mask:0x2
	ds_read_b128 v[52:55], v0 offset:37760
	s_waitcnt lgkmcnt(11)
	v_pk_fma_f32 v[4:5], v[94:95], v[72:73], v[96:97] op_sel_hi:[0,1,1] neg_lo:[1,0,0] neg_hi:[1,0,0]
	v_pk_fma_f32 v[6:7], v[94:95], v[74:75], v[98:99] op_sel_hi:[0,1,1] neg_lo:[1,0,0] neg_hi:[1,0,0]
	s_waitcnt lgkmcnt(9)
	v_pk_mul_f32 v[88:89], v[4:5], v[142:143] op_sel_hi:[0,1]
	v_pk_mul_f32 v[90:91], v[6:7], v[146:147] op_sel_hi:[0,1]
	v_pk_fma_f32 v[88:89], v[4:5], v[144:145], v[88:89] op_sel:[1,0,0] op_sel_hi:[1,1,1]
	v_pk_fma_f32 v[90:91], v[6:7], v[148:149], v[90:91] op_sel:[1,0,0] op_sel_hi:[1,1,1]
	v_pk_add_f32 v[102:103], v[88:89], v[90:91]
	s_waitcnt lgkmcnt(8)
	v_pk_mul_f32 v[96:97], v[82:83], v[154:155] op_sel:[1,0] op_sel_hi:[1,1]
	v_pk_mul_f32 v[98:99], v[82:83], v[156:157] op_sel:[1,0] op_sel_hi:[1,1]
	v_add_f32_dpp v93, v102, v102 quad_perm:[1,0,3,2] row_mask:0xf bank_mask:0xf
	s_waitcnt lgkmcnt(7)
	v_pk_fma_f32 v[96:97], v[4:5], v[138:139], v[96:97]
	v_pk_fma_f32 v[98:99], v[6:7], v[140:141], v[98:99]
	v_add_f32_dpp v92, v93, v93 quad_perm:[2,3,0,1] row_mask:0xf bank_mask:0xf
	ds_read_b128 v[64:67], v0 offset:38528
	ds_read_b128 v[68:71], v0 offset:38784
	v_add_f32_dpp v93, v92, v92 row_ror:4 row_mask:0xf bank_mask:0xf
	ds_read_b128 v[76:79], v0 offset:39296
	ds_read_b128 v[60:63], v0 offset:38272
	v_add_f32_dpp v94, v93, v93 row_ror:8 row_mask:0xf bank_mask:0xf
	v_add_f32_dpp v110, v93, v93 row_ror:8 row_mask:0xf bank_mask:0x8
	ds_read_b128 v[72:75], v0 offset:39040
	s_waitcnt lgkmcnt(11)
	v_pk_fma_f32 v[4:5], v[94:95], v[150:151], v[96:97] op_sel_hi:[0,1,1] neg_lo:[1,0,0] neg_hi:[1,0,0]
	v_pk_fma_f32 v[6:7], v[94:95], v[152:153], v[98:99] op_sel_hi:[0,1,1] neg_lo:[1,0,0] neg_hi:[1,0,0]
	v_add_f32_dpp v133, v133, v133 row_ror:8 row_mask:0xf bank_mask:0x3
	s_nop 1
	v_add_f32_dpp v133, v103, v103 row_ror:8 row_mask:0xf bank_mask:0xc
	v_add_f32_dpp v105, v105, v105 row_half_mirror row_mask:0xf bank_mask:0x5
	s_nop 1
	v_add_f32_dpp v105, v133, v133 row_half_mirror row_mask:0xf bank_mask:0xa
	s_waitcnt lgkmcnt(8)
	v_pk_mul_f32 v[88:89], v[4:5], v[44:45] op_sel_hi:[0,1]
	v_pk_mul_f32 v[90:91], v[6:7], v[48:49] op_sel_hi:[0,1]
	v_pk_fma_f32 v[88:89], v[4:5], v[46:47], v[88:89] op_sel:[1,0,0] op_sel_hi:[1,1,1]
	v_pk_fma_f32 v[90:91], v[6:7], v[50:51], v[90:91] op_sel:[1,0,0] op_sel_hi:[1,1,1]
	v_pk_add_f32 v[134:135], v[88:89], v[90:91]
	s_waitcnt lgkmcnt(7)
	v_pk_mul_f32 v[96:97], v[84:85], v[56:57] op_sel:[0,0] op_sel_hi:[0,1]
	v_pk_mul_f32 v[98:99], v[84:85], v[58:59] op_sel:[0,0] op_sel_hi:[0,1]
	v_add_f32_dpp v93, v134, v134 quad_perm:[1,0,3,2] row_mask:0xf bank_mask:0xf
	s_waitcnt lgkmcnt(6)
	v_pk_fma_f32 v[96:97], v[4:5], v[40:41], v[96:97]
	v_pk_fma_f32 v[98:99], v[6:7], v[42:43], v[98:99]
	v_add_f32_dpp v92, v93, v93 quad_perm:[2,3,0,1] row_mask:0xf bank_mask:0xf
	ds_read_b128 v[142:145], v0 offset:39808
	ds_read_b128 v[146:149], v0 offset:40064
	v_add_f32_dpp v93, v92, v92 row_ror:4 row_mask:0xf bank_mask:0xf
	ds_read_b128 v[154:157], v0 offset:40576
	ds_read_b128 v[138:141], v0 offset:39552
	v_add_f32_dpp v94, v93, v93 row_ror:8 row_mask:0xf bank_mask:0xf
	v_add_f32_dpp v111, v93, v93 row_ror:8 row_mask:0xf bank_mask:0x1
	ds_read_b128 v[150:153], v0 offset:40320
	s_waitcnt lgkmcnt(10)
	v_pk_fma_f32 v[4:5], v[94:95], v[52:53], v[96:97] op_sel_hi:[0,1,1] neg_lo:[1,0,0] neg_hi:[1,0,0]
	v_pk_fma_f32 v[6:7], v[94:95], v[54:55], v[98:99] op_sel_hi:[0,1,1] neg_lo:[1,0,0] neg_hi:[1,0,0]
	s_waitcnt lgkmcnt(8)
	v_pk_mul_f32 v[88:89], v[4:5], v[64:65] op_sel_hi:[0,1]
	v_pk_mul_f32 v[90:91], v[6:7], v[68:69] op_sel_hi:[0,1]
	v_pk_fma_f32 v[88:89], v[4:5], v[66:67], v[88:89] op_sel:[1,0,0] op_sel_hi:[1,1,1]
	v_pk_fma_f32 v[90:91], v[6:7], v[70:71], v[90:91] op_sel:[1,0,0] op_sel_hi:[1,1,1]
	v_pk_add_f32 v[136:137], v[88:89], v[90:91]
	s_waitcnt lgkmcnt(7)
	v_pk_mul_f32 v[96:97], v[84:85], v[76:77] op_sel:[1,0] op_sel_hi:[1,1]
	v_pk_mul_f32 v[98:99], v[84:85], v[78:79] op_sel:[1,0] op_sel_hi:[1,1]
	v_add_f32_dpp v93, v136, v136 quad_perm:[1,0,3,2] row_mask:0xf bank_mask:0xf
	s_waitcnt lgkmcnt(6)
	v_pk_fma_f32 v[96:97], v[4:5], v[60:61], v[96:97]
	v_pk_fma_f32 v[98:99], v[6:7], v[62:63], v[98:99]
	v_add_f32_dpp v92, v93, v93 quad_perm:[2,3,0,1] row_mask:0xf bank_mask:0xf
	ds_read_b128 v[44:47], v0 offset:41088
	ds_read_b128 v[48:51], v0 offset:41344
	v_add_f32_dpp v93, v92, v92 row_ror:4 row_mask:0xf bank_mask:0xf
	ds_read_b128 v[56:59], v0 offset:41856
	ds_read_b128 v[40:43], v0 offset:40832
	v_add_f32_dpp v94, v93, v93 row_ror:8 row_mask:0xf bank_mask:0xf
	v_add_f32_dpp v111, v93, v93 row_ror:8 row_mask:0xf bank_mask:0x4
	ds_read_b128 v[52:55], v0 offset:41600
	s_waitcnt lgkmcnt(10)
; __device__ __forceinline__ float bf2f(unsigned short b) { return __uint_as_float(((unsigned)b) << 16); }
; __device__ __forceinline__ unsigned short f2bf(float f) { unsigned r; asm("v_cvt_pk_bf16_f32 %0, %1, %1" : "=v"(r) : "v"(f)); return (unsigned short)(r & 0xffffu); }
; __device__ __forceinline__ float bflo(unsigned u) { return __uint_as_float(u << 16); }
; template <int VAR>
; __device__ __forceinline__ void rwkv_scan_item(const Params& p, int item, char* ldsraw) {
;     ...
;     for (int q = 0; q < (VAR == 4 ? 0 : 16); q++) {
;       const f32x4 cw = nw, ckk = nkk, ckka = nkka, ck = nk, cwr = nwr; const float cv = nv; const f32x2 ccc = ncc;
;       if (q < 15 && VAR != 3) SCAN_LOAD(q + 1)
;       __builtin_amdgcn_sched_barrier(0);
;       float m0 = mul_s(s0, ckk.x), m1 = mul_s(s2, ckk.z), n0 = mul_s(s0, cwr.x), n1 = mul_s(s2, cwr.z);
;       m0 = fma_s(s1, ckk.y, m0); m1 = fma_s(s3, ckk.w, m1); n0 = fma_s(s1, cwr.y, n0); n1 = fma_s(s3, cwr.w, n1);
;       float psa = add_s(m0, m1), pu = add_s(n0, n1);
;       if (VAR != 2) { psa = row16_sum(psa); pu = row16_sum(pu); }
;       const float t0 = fnma_s(psa, ckka.x, mul_s(cv, ck.x)), t1 = fnma_s(psa, ckka.y, mul_s(cv, ck.y));
;       const float t2 = fnma_s(psa, ckka.z, mul_s(cv, ck.z)), t3 = fnma_s(psa, ckka.w, mul_s(cv, ck.w));
;       s0 = fma_s(s0, cw.x, t0); s1 = fma_s(s1, cw.y, t1); s2 = fma_s(s2, cw.z, t2); s3 = fma_s(s3, cw.w, t3);
;       const float y = fnma_s(psa, ccc.x, fma_s(cv, ccc.y, pu));
;       ykeep = sel_eq(ykeep, y, jl, q);
;     }
;     if (c + 1 < 256) store((c + 1) & 1);
;     __builtin_amdgcn_sched_barrier(0);
;     yout[(size_t)c * 16 * 1024] = f2bf(ykeep);
; __device__ __forceinline__ void rwkv_scan2_item(const Params& p, int item, char* ldsraw) {
;     ...
;   auto store = [&](int bi) {
;     float* d = buf + bi * CH + st * STEP;
;     *(f32x4*)(d + part * 4) = pw;
;     *(f32x4*)(d + 64 + part * 4) = (f32x4){bflo(pkk[0]), bfhi(pkk[0]), bflo(pkk[1]), bfhi(pkk[1])};
;     *(f32x4*)(d + 128 + part * 4) = (f32x4){bflo(pkka[0]), bfhi(pkka[0]), bflo(pkka[1]), bfhi(pkka[1])};
;     *(f32x4*)(d + 192 + part * 4) = (f32x4){bflo(pk[0]), bfhi(pk[0]), bflo(pk[1]), bfhi(pk[1])};
;     *(f32x4*)(d + 256 + part * 4) = (f32x4){bflo(pwr[0]), bfhi(pwr[0]), bflo(pwr[1]), bfhi(pwr[1])};
;     d[320 + part] = ident ? 0.f : bf2f(pv);
;     if (part < 2) d[336 + part] = pc;
;   };
	v_pk_fma_f32 v[4:5], v[94:95], v[72:73], v[96:97] op_sel_hi:[0,1,1] neg_lo:[1,0,0] neg_hi:[1,0,0]
	v_pk_fma_f32 v[6:7], v[94:95], v[74:75], v[98:99] op_sel_hi:[0,1,1] neg_lo:[1,0,0] neg_hi:[1,0,0]
	ds_read_b32 v112, v10 offset:21632
	ds_read_b64 v[114:115], v11 offset:21632
	v_add_f32_dpp v135, v135, v135 row_ror:8 row_mask:0xf bank_mask:0x3
	s_nop 1
	v_add_f32_dpp v135, v137, v137 row_ror:8 row_mask:0xf bank_mask:0xc
	s_waitcnt lgkmcnt(10)
	v_pk_mul_f32 v[88:89], v[4:5], v[142:143] op_sel_hi:[0,1]
	v_pk_mul_f32 v[90:91], v[6:7], v[146:147] op_sel_hi:[0,1]
	v_pk_fma_f32 v[88:89], v[4:5], v[144:145], v[88:89] op_sel:[1,0,0] op_sel_hi:[1,1,1]
	v_pk_fma_f32 v[90:91], v[6:7], v[148:149], v[90:91] op_sel:[1,0,0] op_sel_hi:[1,1,1]
	v_pk_add_f32 v[102:103], v[88:89], v[90:91]
	s_waitcnt lgkmcnt(9)
	v_pk_mul_f32 v[96:97], v[86:87], v[154:155] op_sel:[0,0] op_sel_hi:[0,1]
	v_pk_mul_f32 v[98:99], v[86:87], v[156:157] op_sel:[0,0] op_sel_hi:[0,1]
	v_add_f32_dpp v93, v102, v102 quad_perm:[1,0,3,2] row_mask:0xf bank_mask:0xf
	s_waitcnt lgkmcnt(8)
	v_pk_fma_f32 v[96:97], v[4:5], v[138:139], v[96:97]
	v_pk_fma_f32 v[98:99], v[6:7], v[140:141], v[98:99]
	v_add_f32_dpp v92, v93, v93 quad_perm:[2,3,0,1] row_mask:0xf bank_mask:0xf
	s_nop 1
	v_add_f32_dpp v93, v92, v92 row_ror:4 row_mask:0xf bank_mask:0xf
	s_nop 1
	v_add_f32_dpp v94, v93, v93 row_ror:8 row_mask:0xf bank_mask:0xf
	v_add_f32_dpp v111, v93, v93 row_ror:8 row_mask:0xf bank_mask:0x2
	s_waitcnt lgkmcnt(7)
	v_pk_fma_f32 v[4:5], v[94:95], v[150:151], v[96:97] op_sel_hi:[0,1,1] neg_lo:[1,0,0] neg_hi:[1,0,0]
	v_pk_fma_f32 v[6:7], v[94:95], v[152:153], v[98:99] op_sel_hi:[0,1,1] neg_lo:[1,0,0] neg_hi:[1,0,0]
	s_waitcnt lgkmcnt(5)
	v_pk_mul_f32 v[88:89], v[4:5], v[44:45] op_sel_hi:[0,1]
	v_pk_mul_f32 v[90:91], v[6:7], v[48:49] op_sel_hi:[0,1]
	v_pk_fma_f32 v[88:89], v[4:5], v[46:47], v[88:89] op_sel:[1,0,0] op_sel_hi:[1,1,1]
	v_pk_fma_f32 v[90:91], v[6:7], v[50:51], v[90:91] op_sel:[1,0,0] op_sel_hi:[1,1,1]
	v_pk_add_f32 v[132:133], v[88:89], v[90:91]
	s_waitcnt lgkmcnt(4)
	v_pk_mul_f32 v[96:97], v[86:87], v[56:57] op_sel:[1,0] op_sel_hi:[1,1]
	v_pk_mul_f32 v[98:99], v[86:87], v[58:59] op_sel:[1,0] op_sel_hi:[1,1]
	v_add_f32_dpp v93, v132, v132 quad_perm:[1,0,3,2] row_mask:0xf bank_mask:0xf
	s_waitcnt lgkmcnt(3)
	v_pk_fma_f32 v[96:97], v[4:5], v[40:41], v[96:97]
	v_pk_fma_f32 v[98:99], v[6:7], v[42:43], v[98:99]
	v_add_f32_dpp v92, v93, v93 quad_perm:[2,3,0,1] row_mask:0xf bank_mask:0xf
	s_nop 1
	v_add_f32_dpp v93, v92, v92 row_ror:4 row_mask:0xf bank_mask:0xf
	s_nop 1
	v_add_f32_dpp v94, v93, v93 row_ror:8 row_mask:0xf bank_mask:0xf
	v_add_f32_dpp v111, v93, v93 row_ror:8 row_mask:0xf bank_mask:0x8
	s_waitcnt lgkmcnt(2)
	v_pk_fma_f32 v[4:5], v[94:95], v[52:53], v[96:97] op_sel_hi:[0,1,1] neg_lo:[1,0,0] neg_hi:[1,0,0]
	v_pk_fma_f32 v[6:7], v[94:95], v[54:55], v[98:99] op_sel_hi:[0,1,1] neg_lo:[1,0,0] neg_hi:[1,0,0]
	v_add_f32_dpp v103, v103, v103 row_ror:8 row_mask:0xf bank_mask:0x3
	s_nop 1
	v_add_f32_dpp v103, v133, v133 row_ror:8 row_mask:0xf bank_mask:0xc
	v_add_f32_dpp v135, v135, v135 row_half_mirror row_mask:0xf bank_mask:0x5
	s_nop 1
	v_add_f32_dpp v135, v103, v103 row_half_mirror row_mask:0xf bank_mask:0xa
	v_cndmask_b32_e64 v106, v135, v105, s[36:37]
	v_cndmask_b32_e64 v107, v105, v135, s[36:37]
	s_nop 1
	v_add_f32_dpp v105, v106, v107 quad_perm:[2,3,0,1] row_mask:0xf bank_mask:0xf
	v_cndmask_b32_e64 v106, v105, v101, s[34:35]
	v_cndmask_b32_e64 v107, v101, v105, s[34:35]
	s_nop 1
	v_add_f32_dpp v101, v106, v107 quad_perm:[1,0,3,2] row_mask:0xf bank_mask:0xf
	v_cndmask_b32_e64 v106, v108, v110, s[34:35]
	v_cndmask_b32_e64 v107, v109, v111, s[34:35]
	v_cndmask_b32_e64 v106, v106, v107, s[36:37]
	s_waitcnt lgkmcnt(0)
	v_fma_f32 v101, v112, v115, v101
	v_fma_f32 v101, -v106, v114, v101
	v_cvt_pk_bf16_f32 v107, v101, v101
	global_store_short v16, v107, s[30:31]
	s_cmp_eq_u32 s38, 63
	s_cbranch_scc1 .Lsc_o_nost
	s_waitcnt vmcnt(1)
	ds_write_b128 v2, v[20:23] offset:0
	v_lshlrev_b32_e32 v36, 16, v24
	v_lshlrev_b32_e32 v37, 16, v30
	v_and_b32_e32 v38, 0xffff0000, v24
	v_and_b32_e32 v39, 0xffff0000, v30
	ds_write_b128 v2, v[36:39] offset:256
	v_lshlrev_b32_e32 v40, 16, v25
	v_lshlrev_b32_e32 v41, 16, v31
	v_and_b32_e32 v42, 0xffff0000, v25
	v_and_b32_e32 v43, 0xffff0000, v31
	ds_write_b128 v2, v[40:43] offset:512
	v_lshlrev_b32_e32 v44, 16, v26
	v_and_b32_e32 v45, 0xffff0000, v26
	v_lshlrev_b32_e32 v46, 16, v27
	v_and_b32_e32 v47, 0xffff0000, v27
	ds_write_b128 v2, v[44:47] offset:768
	v_lshlrev_b32_e32 v48, 16, v28
	v_and_b32_e32 v49, 0xffff0000, v28
	v_lshlrev_b32_e32 v50, 16, v29
	v_and_b32_e32 v51, 0xffff0000, v29
	ds_write_b128 v2, v[48:51] offset:1024
	v_lshlrev_b32_e32 v52, 16, v32
	s_cmp_eq_u32 s41, 2
	s_cselect_b32 s2, 0, -1
	v_and_b32_e32 v52, s2, v52
	ds_write_b32 v8, v52 offset:0
	s_mov_b32 s2, 0x00010001
	s_mov_b32 s3, 0x00010001
	s_mov_b64 exec, s[2:3]
	ds_write_b64 v9, v[34:35] offset:0
	s_mov_b64 exec, -1
